# attention Q.K^T: K fragments read up to 11 ahead into free temporaries, counted lgkmcnt waits (on top of v64)
# baseline (speedup 1.0000x reference)
.LBB0_98:
	s_or_b64 exec, exec, s[24:25]
	s_waitcnt vmcnt(0)
	v_bfe_u32 v34, v30, 16, 1
	v_add3_u32 v30, v30, v34, s60
	v_bfe_u32 v34, v31, 16, 1
	v_lshrrev_b32_e32 v30, 16, v30
	v_add3_u32 v31, v31, v34, s60
	v_and_or_b32 v34, v31, s33, v30
	v_bfe_u32 v30, v32, 16, 1
	v_add3_u32 v30, v32, v30, s60
	v_bfe_u32 v31, v33, 16, 1
	v_lshrrev_b32_e32 v30, 16, v30
	v_add3_u32 v31, v33, v31, s60
	v_and_or_b32 v35, v31, s33, v30
	v_bfe_u32 v30, v26, 16, 1
	v_add3_u32 v26, v26, v30, s60
	v_bfe_u32 v30, v27, 16, 1
	v_lshrrev_b32_e32 v26, 16, v26
	v_add3_u32 v27, v27, v30, s60
	v_and_or_b32 v36, v27, s33, v26
	v_bfe_u32 v26, v28, 16, 1
	v_add3_u32 v26, v28, v26, s60
	v_bfe_u32 v27, v29, 16, 1
	v_lshrrev_b32_e32 v26, 16, v26
	v_add3_u32 v27, v29, v27, s60
	v_and_or_b32 v37, v27, s33, v26
	v_bfe_u32 v26, v18, 16, 1
	v_add3_u32 v18, v18, v26, s60
	v_bfe_u32 v26, v19, 16, 1
	v_lshrrev_b32_e32 v18, 16, v18
	v_add3_u32 v19, v19, v26, s60
	v_and_or_b32 v66, v19, s33, v18
	v_bfe_u32 v18, v20, 16, 1
	v_add3_u32 v18, v20, v18, s60
	v_bfe_u32 v19, v21, 16, 1
	v_lshrrev_b32_e32 v18, 16, v18
	v_add3_u32 v19, v21, v19, s60
	v_and_or_b32 v67, v19, s33, v18
	v_bfe_u32 v18, v10, 16, 1
	v_add3_u32 v10, v10, v18, s60
	v_bfe_u32 v18, v11, 16, 1
	v_lshrrev_b32_e32 v10, 16, v10
	v_add3_u32 v11, v11, v18, s60
	v_and_or_b32 v68, v11, s33, v10
	v_bfe_u32 v10, v12, 16, 1
	v_add3_u32 v10, v12, v10, s60
	v_bfe_u32 v11, v13, 16, 1
	v_lshrrev_b32_e32 v10, 16, v10
	v_add3_u32 v11, v13, v11, s60
	v_and_or_b32 v69, v11, s33, v10
	v_bfe_u32 v10, v6, 16, 1
	v_add3_u32 v6, v6, v10, s60
	v_bfe_u32 v10, v7, 16, 1
	v_lshrrev_b32_e32 v6, 16, v6
	v_add3_u32 v7, v7, v10, s60
	v_and_or_b32 v70, v7, s33, v6
	v_bfe_u32 v6, v8, 16, 1
	v_add3_u32 v6, v8, v6, s60
	v_bfe_u32 v7, v9, 16, 1
	v_lshrrev_b32_e32 v6, 16, v6
	v_add3_u32 v7, v9, v7, s60
	v_and_or_b32 v71, v7, s33, v6
	v_bfe_u32 v6, v2, 16, 1
	v_add3_u32 v2, v2, v6, s60
	v_bfe_u32 v6, v3, 16, 1
	v_lshrrev_b32_e32 v2, 16, v2
	v_add3_u32 v3, v3, v6, s60
	v_and_or_b32 v72, v3, s33, v2
	v_bfe_u32 v2, v4, 16, 1
	v_add3_u32 v2, v4, v2, s60
	v_bfe_u32 v3, v5, 16, 1
	v_lshrrev_b32_e32 v2, 16, v2
	v_add3_u32 v3, v5, v3, s60
	v_and_or_b32 v73, v3, s33, v2
	v_bfe_u32 v2, v22, 16, 1
	v_add3_u32 v2, v22, v2, s60
	v_bfe_u32 v3, v23, 16, 1
	v_lshrrev_b32_e32 v2, 16, v2
	v_add3_u32 v3, v23, v3, s60
	v_and_or_b32 v74, v3, s33, v2
	v_bfe_u32 v2, v24, 16, 1
	v_add3_u32 v2, v24, v2, s60
	v_bfe_u32 v3, v25, 16, 1
	v_lshrrev_b32_e32 v2, 16, v2
	v_add3_u32 v3, v25, v3, s60
	v_and_or_b32 v75, v3, s33, v2
	v_bfe_u32 v2, v14, 16, 1
	v_add3_u32 v2, v14, v2, s60
	v_bfe_u32 v3, v15, 16, 1
	v_lshrrev_b32_e32 v2, 16, v2
	v_add3_u32 v3, v15, v3, s60
	v_and_or_b32 v76, v3, s33, v2
	v_bfe_u32 v2, v16, 16, 1
	v_add3_u32 v2, v16, v2, s60
	v_bfe_u32 v3, v17, 16, 1
	v_lshrrev_b32_e32 v2, 16, v2
	v_add3_u32 v3, v17, v3, s60
	v_and_or_b32 v77, v3, s33, v2
	s_mov_b32 s1, 0xff61b1e6
	s_lshl_b32 s46, s0, 1
	ds_read_b128 v[180:183], v140
	ds_read_b128 v[184:187], v140 offset:64
	ds_read_b128 v[188:191], v140 offset:128
	ds_read_b128 v[192:195], v140 offset:192
	ds_read_b128 v[196:199], v140 offset:4352
	ds_read_b128 v[220:223], v140 offset:4416
	ds_read_b128 v[224:227], v140 offset:4480
	ds_read_b128 v[228:231], v140 offset:4544
	ds_read_b128 v[232:235], v140 offset:8704
	ds_read_b128 v[236:239], v140 offset:8768
	ds_read_b128 v[240:243], v140 offset:8832
	ds_read_b128 v[244:247], v140 offset:8896
	s_waitcnt lgkmcnt(11)
	v_mfma_f32_16x16x32_bf16 v[2:5], v[180:183], v[70:73], 0
	ds_read_b128 v[180:183], v140 offset:13056
	s_waitcnt lgkmcnt(11)
	v_mfma_f32_16x16x32_bf16 v[2:5], v[184:187], v[66:69], v[2:5]
	ds_read_b128 v[184:187], v140 offset:13120
	s_waitcnt lgkmcnt(11)
	v_mfma_f32_16x16x32_bf16 v[2:5], v[188:191], v[34:37], v[2:5]
	ds_read_b128 v[188:191], v140 offset:13184
	s_waitcnt lgkmcnt(11)
	v_mfma_f32_16x16x32_bf16 v[2:5], v[192:195], v[74:77], v[2:5]
	ds_read_b128 v[192:195], v140 offset:13248
	s_waitcnt lgkmcnt(11)
	v_mfma_f32_16x16x32_bf16 v[62:65], v[196:199], v[70:73], 0
	ds_read_b128 v[196:199], v140 offset:17408
	s_waitcnt lgkmcnt(11)
	v_mfma_f32_16x16x32_bf16 v[62:65], v[220:223], v[66:69], v[62:65]
	ds_read_b128 v[220:223], v140 offset:17472
	s_waitcnt lgkmcnt(11)
	v_mfma_f32_16x16x32_bf16 v[62:65], v[224:227], v[34:37], v[62:65]
	ds_read_b128 v[224:227], v140 offset:17536
	s_waitcnt lgkmcnt(11)
	v_mfma_f32_16x16x32_bf16 v[62:65], v[228:231], v[74:77], v[62:65]
	ds_read_b128 v[228:231], v140 offset:17600
	s_waitcnt lgkmcnt(11)
	v_mfma_f32_16x16x32_bf16 v[6:9], v[232:235], v[70:73], 0
	ds_read_b128 v[232:235], v140 offset:21760
	s_waitcnt lgkmcnt(11)
	v_mfma_f32_16x16x32_bf16 v[6:9], v[236:239], v[66:69], v[6:9]
	ds_read_b128 v[236:239], v140 offset:21824
	s_waitcnt lgkmcnt(11)
	v_mfma_f32_16x16x32_bf16 v[6:9], v[240:243], v[34:37], v[6:9]
	ds_read_b128 v[240:243], v140 offset:21888
	s_waitcnt lgkmcnt(11)
	v_mfma_f32_16x16x32_bf16 v[6:9], v[244:247], v[74:77], v[6:9]
	ds_read_b128 v[244:247], v140 offset:21952
	s_waitcnt lgkmcnt(11)
	v_mfma_f32_16x16x32_bf16 v[58:61], v[180:183], v[70:73], 0
	ds_read_b128 v[180:183], v140 offset:26112
	s_waitcnt lgkmcnt(11)
	v_mfma_f32_16x16x32_bf16 v[58:61], v[184:187], v[66:69], v[58:61]
	ds_read_b128 v[184:187], v140 offset:26176
	s_waitcnt lgkmcnt(11)
	v_mfma_f32_16x16x32_bf16 v[58:61], v[188:191], v[34:37], v[58:61]
	ds_read_b128 v[188:191], v140 offset:26240
	s_waitcnt lgkmcnt(11)
	v_mfma_f32_16x16x32_bf16 v[58:61], v[192:195], v[74:77], v[58:61]
	ds_read_b128 v[192:195], v140 offset:26304
	s_waitcnt lgkmcnt(11)
	v_mfma_f32_16x16x32_bf16 v[10:13], v[196:199], v[70:73], 0
	ds_read_b128 v[196:199], v140 offset:30464
	s_waitcnt lgkmcnt(11)
	v_mfma_f32_16x16x32_bf16 v[10:13], v[220:223], v[66:69], v[10:13]
	ds_read_b128 v[220:223], v140 offset:30528
	s_waitcnt lgkmcnt(11)
	v_mfma_f32_16x16x32_bf16 v[10:13], v[224:227], v[34:37], v[10:13]
	ds_read_b128 v[224:227], v140 offset:30592
	s_waitcnt lgkmcnt(11)
	v_mfma_f32_16x16x32_bf16 v[10:13], v[228:231], v[74:77], v[10:13]
	ds_read_b128 v[228:231], v140 offset:30656
	s_waitcnt lgkmcnt(11)
	v_mfma_f32_16x16x32_bf16 v[54:57], v[232:235], v[70:73], 0
	ds_read_b128 v[232:235], v140 offset:34816
	s_waitcnt lgkmcnt(11)
	v_mfma_f32_16x16x32_bf16 v[54:57], v[236:239], v[66:69], v[54:57]
	ds_read_b128 v[236:239], v140 offset:34880
	s_waitcnt lgkmcnt(11)
	v_mfma_f32_16x16x32_bf16 v[54:57], v[240:243], v[34:37], v[54:57]
	ds_read_b128 v[240:243], v140 offset:34944
	s_waitcnt lgkmcnt(11)
	v_mfma_f32_16x16x32_bf16 v[54:57], v[244:247], v[74:77], v[54:57]
	ds_read_b128 v[244:247], v140 offset:35008
	s_waitcnt lgkmcnt(11)
	v_mfma_f32_16x16x32_bf16 v[14:17], v[180:183], v[70:73], 0
	ds_read_b128 v[180:183], v140 offset:39168
	s_waitcnt lgkmcnt(11)
	v_mfma_f32_16x16x32_bf16 v[14:17], v[184:187], v[66:69], v[14:17]
	ds_read_b128 v[184:187], v140 offset:39232
	s_waitcnt lgkmcnt(11)
	v_mfma_f32_16x16x32_bf16 v[14:17], v[188:191], v[34:37], v[14:17]
	ds_read_b128 v[188:191], v140 offset:39296
	s_waitcnt lgkmcnt(11)
	v_mfma_f32_16x16x32_bf16 v[14:17], v[192:195], v[74:77], v[14:17]
	ds_read_b128 v[192:195], v140 offset:39360
	s_waitcnt lgkmcnt(11)
	v_mfma_f32_16x16x32_bf16 v[50:53], v[196:199], v[70:73], 0
	ds_read_b128 v[196:199], v140 offset:43520
	s_waitcnt lgkmcnt(11)
	v_mfma_f32_16x16x32_bf16 v[50:53], v[220:223], v[66:69], v[50:53]
	ds_read_b128 v[220:223], v140 offset:43584
	s_waitcnt lgkmcnt(11)
	v_mfma_f32_16x16x32_bf16 v[50:53], v[224:227], v[34:37], v[50:53]
	ds_read_b128 v[224:227], v140 offset:43648
	s_waitcnt lgkmcnt(11)
	v_mfma_f32_16x16x32_bf16 v[50:53], v[228:231], v[74:77], v[50:53]
	ds_read_b128 v[228:231], v140 offset:43712
	s_waitcnt lgkmcnt(11)
	v_mfma_f32_16x16x32_bf16 v[18:21], v[232:235], v[70:73], 0
	ds_read_b128 v[232:235], v140 offset:47872
	s_waitcnt lgkmcnt(11)
	v_mfma_f32_16x16x32_bf16 v[18:21], v[236:239], v[66:69], v[18:21]
	ds_read_b128 v[236:239], v140 offset:47936
	s_waitcnt lgkmcnt(11)
	v_mfma_f32_16x16x32_bf16 v[18:21], v[240:243], v[34:37], v[18:21]
	ds_read_b128 v[240:243], v140 offset:48000
	s_waitcnt lgkmcnt(11)
	v_mfma_f32_16x16x32_bf16 v[18:21], v[244:247], v[74:77], v[18:21]
	ds_read_b128 v[244:247], v140 offset:48064
	s_waitcnt lgkmcnt(11)
	v_mfma_f32_16x16x32_bf16 v[46:49], v[180:183], v[70:73], 0
	ds_read_b128 v[180:183], v140 offset:52224
	s_waitcnt lgkmcnt(11)
	v_mfma_f32_16x16x32_bf16 v[46:49], v[184:187], v[66:69], v[46:49]
	ds_read_b128 v[184:187], v140 offset:52288
	s_waitcnt lgkmcnt(11)
	v_mfma_f32_16x16x32_bf16 v[46:49], v[188:191], v[34:37], v[46:49]
	ds_read_b128 v[188:191], v140 offset:52352
	s_waitcnt lgkmcnt(11)
	v_mfma_f32_16x16x32_bf16 v[46:49], v[192:195], v[74:77], v[46:49]
	ds_read_b128 v[192:195], v140 offset:52416
	s_waitcnt lgkmcnt(11)
	v_mfma_f32_16x16x32_bf16 v[22:25], v[196:199], v[70:73], 0
	ds_read_b128 v[196:199], v140 offset:56576
	s_waitcnt lgkmcnt(11)
	v_mfma_f32_16x16x32_bf16 v[22:25], v[220:223], v[66:69], v[22:25]
	ds_read_b128 v[220:223], v140 offset:56640
	s_waitcnt lgkmcnt(11)
	v_mfma_f32_16x16x32_bf16 v[22:25], v[224:227], v[34:37], v[22:25]
	ds_read_b128 v[224:227], v140 offset:56704
	s_waitcnt lgkmcnt(11)
	v_mfma_f32_16x16x32_bf16 v[22:25], v[228:231], v[74:77], v[22:25]
	ds_read_b128 v[228:231], v140 offset:56768
	s_waitcnt lgkmcnt(11)
	v_mfma_f32_16x16x32_bf16 v[42:45], v[232:235], v[70:73], 0
	ds_read_b128 v[232:235], v140 offset:60928
	s_waitcnt lgkmcnt(11)
	v_mfma_f32_16x16x32_bf16 v[42:45], v[236:239], v[66:69], v[42:45]
	ds_read_b128 v[236:239], v140 offset:60992
	s_waitcnt lgkmcnt(11)
	v_mfma_f32_16x16x32_bf16 v[42:45], v[240:243], v[34:37], v[42:45]
	ds_read_b128 v[240:243], v140 offset:61056
	s_waitcnt lgkmcnt(11)
	v_mfma_f32_16x16x32_bf16 v[42:45], v[244:247], v[74:77], v[42:45]
	ds_read_b128 v[244:247], v140 offset:61120
	s_waitcnt lgkmcnt(11)
	v_mfma_f32_16x16x32_bf16 v[26:29], v[180:183], v[70:73], 0
	ds_read_b128 v[180:183], v140 offset:65280
	s_waitcnt lgkmcnt(11)
	v_mfma_f32_16x16x32_bf16 v[26:29], v[184:187], v[66:69], v[26:29]
	ds_read_b128 v[184:187], v140 offset:65344
	s_waitcnt lgkmcnt(11)
	v_mfma_f32_16x16x32_bf16 v[26:29], v[188:191], v[34:37], v[26:29]
	ds_read_b128 v[188:191], v140 offset:65408
	s_waitcnt lgkmcnt(11)
	v_mfma_f32_16x16x32_bf16 v[26:29], v[192:195], v[74:77], v[26:29]
	ds_read_b128 v[192:195], v140 offset:65472
	s_waitcnt lgkmcnt(11)
	v_mfma_f32_16x16x32_bf16 v[38:41], v[196:199], v[70:73], 0
	s_waitcnt lgkmcnt(10)
	v_mfma_f32_16x16x32_bf16 v[38:41], v[220:223], v[66:69], v[38:41]
	s_waitcnt lgkmcnt(9)
	v_mfma_f32_16x16x32_bf16 v[38:41], v[224:227], v[34:37], v[38:41]
	s_waitcnt lgkmcnt(8)
	v_mfma_f32_16x16x32_bf16 v[38:41], v[228:231], v[74:77], v[38:41]
	s_waitcnt lgkmcnt(7)
	v_mfma_f32_16x16x32_bf16 v[30:33], v[232:235], v[70:73], 0
	s_waitcnt lgkmcnt(6)
	v_mfma_f32_16x16x32_bf16 v[30:33], v[236:239], v[66:69], v[30:33]
	s_waitcnt lgkmcnt(5)
	v_mfma_f32_16x16x32_bf16 v[30:33], v[240:243], v[34:37], v[30:33]
	s_waitcnt lgkmcnt(4)
	v_mfma_f32_16x16x32_bf16 v[30:33], v[244:247], v[74:77], v[30:33]
	s_waitcnt lgkmcnt(3)
	v_mfma_f32_16x16x32_bf16 v[70:73], v[180:183], v[70:73], 0
	s_waitcnt lgkmcnt(2)
	v_mfma_f32_16x16x32_bf16 v[66:69], v[184:187], v[66:69], v[70:73]
	s_waitcnt lgkmcnt(1)
	v_mfma_f32_16x16x32_bf16 v[34:37], v[188:191], v[34:37], v[66:69]
	s_waitcnt lgkmcnt(0)
	v_mfma_f32_16x16x32_bf16 v[34:37], v[192:195], v[74:77], v[34:37]
	v_max_f32_e32 v66, v5, v5
	v_max_f32_e32 v67, v4, v4
	v_max_f32_e32 v66, v67, v66
	v_max_f32_e32 v67, v65, v65
	v_max_f32_e32 v68, v64, v64
	v_max_f32_e32 v67, v68, v67
	v_max3_f32 v66, v2, v3, v66
	v_max3_f32 v67, v62, v63, v67
	v_max3_f32 v66, v66, s1, v67
	v_max_f32_e32 v67, v9, v9
	v_max_f32_e32 v68, v8, v8
	v_max_f32_e32 v67, v68, v67
	v_max_f32_e32 v68, v61, v61
	v_max_f32_e32 v69, v60, v60
	v_max_f32_e32 v68, v69, v68
	v_max3_f32 v67, v6, v7, v67
	v_max3_f32 v68, v58, v59, v68
	v_max3_f32 v66, v66, v67, v68
	v_max_f32_e32 v67, v13, v13
	v_max_f32_e32 v68, v12, v12
	v_max_f32_e32 v67, v68, v67
	v_max_f32_e32 v68, v57, v57
	v_max_f32_e32 v69, v56, v56
	v_max_f32_e32 v68, v69, v68
	v_max3_f32 v67, v10, v11, v67
	v_max3_f32 v68, v54, v55, v68
	v_max3_f32 v66, v66, v67, v68
	v_max_f32_e32 v67, v17, v17
	v_max_f32_e32 v68, v16, v16
	v_max_f32_e32 v67, v68, v67
	v_max_f32_e32 v68, v53, v53
	v_max_f32_e32 v69, v52, v52
	v_max_f32_e32 v68, v69, v68
	v_max3_f32 v67, v14, v15, v67
	v_max3_f32 v68, v50, v51, v68
	v_max3_f32 v66, v66, v67, v68
	v_max_f32_e32 v67, v21, v21
	v_max_f32_e32 v68, v20, v20
	v_max_f32_e32 v67, v68, v67
	v_max_f32_e32 v68, v49, v49
	v_max_f32_e32 v69, v48, v48
	v_max_f32_e32 v68, v69, v68
	v_max3_f32 v67, v18, v19, v67
	v_max3_f32 v68, v46, v47, v68
	v_max3_f32 v66, v66, v67, v68
	v_max_f32_e32 v67, v25, v25
	v_max_f32_e32 v68, v24, v24
	v_max_f32_e32 v67, v68, v67
	v_max_f32_e32 v68, v45, v45
	v_max_f32_e32 v69, v44, v44
	v_max_f32_e32 v68, v69, v68
	v_max3_f32 v67, v22, v23, v67
	v_max3_f32 v68, v42, v43, v68
	v_max3_f32 v66, v66, v67, v68
	v_max_f32_e32 v67, v29, v29
	v_max_f32_e32 v68, v28, v28
	v_max_f32_e32 v67, v68, v67
	v_max_f32_e32 v68, v41, v41
	v_max_f32_e32 v69, v40, v40
	v_max_f32_e32 v68, v69, v68
	v_max3_f32 v67, v26, v27, v67
	v_max3_f32 v68, v38, v39, v68
	v_max3_f32 v66, v66, v67, v68
	v_max_f32_e32 v67, v33, v33
	v_max_f32_e32 v68, v32, v32
	v_max_f32_e32 v67, v68, v67
	v_max_f32_e32 v68, v37, v37
	v_max_f32_e32 v69, v36, v36
	v_max_f32_e32 v68, v69, v68
	v_max3_f32 v67, v30, v31, v67
	v_max3_f32 v68, v34, v35, v68
	v_max3_f32 v67, v66, v67, v68
	v_and_b32_e32 v68, 64, v206
	v_xor_b32_e32 v66, 16, v206
	v_add_u32_e32 v68, 64, v68
	v_cmp_lt_i32_e32 vcc, v66, v68
	s_mov_b32 s1, 0xc2fc0000
	s_nop 0
	v_cndmask_b32_e32 v66, v206, v66, vcc
	v_lshlrev_b32_e32 v66, 2, v66
	ds_bpermute_b32 v69, v66, v67
	s_waitcnt lgkmcnt(0)
	v_max_f32_e32 v69, v69, v69
	v_max_f32_e32 v69, v67, v69
	v_xor_b32_e32 v67, 32, v206
	v_cmp_lt_i32_e32 vcc, v67, v68
	s_nop 1
	v_cndmask_b32_e32 v67, v206, v67, vcc
	v_lshlrev_b32_e32 v67, 2, v67
	ds_bpermute_b32 v68, v67, v69
	s_waitcnt lgkmcnt(0)
	v_max_f32_e32 v68, v68, v68
	v_max_f32_e32 v68, v69, v68
	v_sub_f32_e32 v2, v2, v68
	v_mul_f32_e32 v69, 0x3e0293ee, v2
	v_cmp_gt_f32_e32 vcc, s1, v69
	v_sub_f32_e32 v62, v62, v68
	v_sub_f32_e32 v3, v3, v68
	v_cndmask_b32_e32 v69, 0, v207, vcc
	v_fmac_f32_e32 v69, 0x3e0293ee, v2
	v_exp_f32_e32 v2, v69
	v_cndmask_b32_e32 v69, 0, v208, vcc
	v_sub_f32_e32 v63, v63, v68
	v_sub_f32_e32 v4, v4, v68
	v_ldexp_f32 v2, v2, v69
	v_mul_f32_e32 v69, 0x3e0293ee, v62
	v_cmp_gt_f32_e32 vcc, s1, v69
	v_sub_f32_e32 v64, v64, v68
	v_sub_f32_e32 v5, v5, v68
	v_cndmask_b32_e32 v69, 0, v207, vcc
	v_fmac_f32_e32 v69, 0x3e0293ee, v62
	v_exp_f32_e32 v62, v69
	v_cndmask_b32_e32 v69, 0, v208, vcc
	v_sub_f32_e32 v65, v65, v68
	v_sub_f32_e32 v6, v6, v68
	v_ldexp_f32 v62, v62, v69
	v_mul_f32_e32 v69, 0x3e0293ee, v3
	v_cmp_gt_f32_e32 vcc, s1, v69
	v_sub_f32_e32 v58, v58, v68
	v_sub_f32_e32 v7, v7, v68
	v_cndmask_b32_e32 v69, 0, v207, vcc
	v_fmac_f32_e32 v69, 0x3e0293ee, v3
	v_exp_f32_e32 v3, v69
	v_cndmask_b32_e32 v69, 0, v208, vcc
	v_sub_f32_e32 v59, v59, v68
	v_sub_f32_e32 v8, v8, v68
	v_ldexp_f32 v3, v3, v69
	v_mul_f32_e32 v69, 0x3e0293ee, v63
	v_cmp_gt_f32_e32 vcc, s1, v69
	v_bfe_u32 v73, v3, 16, 1
	v_add3_u32 v73, v3, v73, s60
	v_cndmask_b32_e32 v69, 0, v207, vcc
	v_fmac_f32_e32 v69, 0x3e0293ee, v63
	v_exp_f32_e32 v63, v69
	v_cndmask_b32_e32 v69, 0, v208, vcc
	v_sub_f32_e32 v60, v60, v68
	v_sub_f32_e32 v9, v9, v68
	v_ldexp_f32 v63, v63, v69
	v_mul_f32_e32 v69, 0x3e0293ee, v4
	v_cmp_gt_f32_e32 vcc, s1, v69
	v_sub_f32_e32 v61, v61, v68
	v_sub_f32_e32 v10, v10, v68
	v_cndmask_b32_e32 v69, 0, v207, vcc
	v_fmac_f32_e32 v69, 0x3e0293ee, v4
	v_exp_f32_e32 v4, v69
	v_cndmask_b32_e32 v69, 0, v208, vcc
	v_sub_f32_e32 v54, v54, v68
	v_sub_f32_e32 v11, v11, v68
	v_ldexp_f32 v4, v4, v69
	v_mul_f32_e32 v69, 0x3e0293ee, v64
	v_cmp_gt_f32_e32 vcc, s1, v69
	v_sub_f32_e32 v55, v55, v68
	v_sub_f32_e32 v12, v12, v68
	v_cndmask_b32_e32 v69, 0, v207, vcc
	v_fmac_f32_e32 v69, 0x3e0293ee, v64
	v_exp_f32_e32 v64, v69
	v_cndmask_b32_e32 v69, 0, v208, vcc
	v_sub_f32_e32 v56, v56, v68
	v_sub_f32_e32 v13, v13, v68
	v_ldexp_f32 v64, v64, v69
	v_mul_f32_e32 v69, 0x3e0293ee, v5
	v_cmp_gt_f32_e32 vcc, s1, v69
	v_sub_f32_e32 v57, v57, v68
	v_sub_f32_e32 v14, v14, v68
	v_cndmask_b32_e32 v69, 0, v207, vcc
	v_fmac_f32_e32 v69, 0x3e0293ee, v5
	v_exp_f32_e32 v5, v69
	v_cndmask_b32_e32 v69, 0, v208, vcc
	v_sub_f32_e32 v50, v50, v68
	v_sub_f32_e32 v15, v15, v68
	v_ldexp_f32 v5, v5, v69
	v_mul_f32_e32 v69, 0x3e0293ee, v65
	v_cmp_gt_f32_e32 vcc, s1, v69
	v_add_f32_e32 v70, v4, v5
	v_bfe_u32 v72, v5, 16, 1
	v_cndmask_b32_e32 v69, 0, v207, vcc
	v_fmac_f32_e32 v69, 0x3e0293ee, v65
	v_exp_f32_e32 v65, v69
	v_cndmask_b32_e32 v69, 0, v208, vcc
	v_sub_f32_e32 v51, v51, v68
	v_sub_f32_e32 v16, v16, v68
	v_ldexp_f32 v65, v65, v69
	v_add_f32_e32 v69, v2, v3
	v_add_f32_e32 v69, v69, v70
	v_add_f32_e32 v70, v62, v63
	v_add_f32_e32 v71, v64, v65
	v_add_f32_e32 v70, v70, v71
	v_add_f32_e32 v69, v69, v70
	v_bfe_u32 v70, v65, 16, 1
	v_bfe_u32 v71, v63, 16, 1
	v_add3_u32 v3, v5, v72, s60
	v_add3_u32 v63, v63, v71, s60
	v_add3_u32 v5, v65, v70, s60
	v_bfe_u32 v70, v4, 16, 1
	v_bfe_u32 v71, v62, 16, 1
	v_bfe_u32 v72, v64, 16, 1
	v_bfe_u32 v65, v2, 16, 1
	v_add3_u32 v64, v64, v72, s60
	v_add3_u32 v62, v62, v71, s60
	v_add3_u32 v4, v4, v70, s60
	v_add3_u32 v2, v2, v65, s60
	v_lshrrev_b32_e32 v65, 16, v4
	v_lshrrev_b32_e32 v4, 16, v62
	v_lshrrev_b32_e32 v62, 16, v64
	v_and_or_b32 v5, v5, s33, v62
	v_mul_f32_e32 v62, 0x3e0293ee, v6
	v_cmp_gt_f32_e32 vcc, s1, v62
	v_and_or_b32 v4, v63, s33, v4
	v_and_or_b32 v3, v3, s33, v65
	v_cndmask_b32_e32 v62, 0, v207, vcc
	v_fmac_f32_e32 v62, 0x3e0293ee, v6
	v_exp_f32_e32 v6, v62
	v_cndmask_b32_e32 v62, 0, v208, vcc
	v_sub_f32_e32 v52, v52, v68
	v_sub_f32_e32 v17, v17, v68
	v_ldexp_f32 v6, v6, v62
	v_mul_f32_e32 v62, 0x3e0293ee, v58
	v_cmp_gt_f32_e32 vcc, s1, v62
	v_sub_f32_e32 v53, v53, v68
	v_sub_f32_e32 v18, v18, v68
	v_cndmask_b32_e32 v62, 0, v207, vcc
	v_fmac_f32_e32 v62, 0x3e0293ee, v58
	v_exp_f32_e32 v58, v62
	v_cndmask_b32_e32 v62, 0, v208, vcc
	v_sub_f32_e32 v46, v46, v68
	v_sub_f32_e32 v19, v19, v68
	v_ldexp_f32 v58, v58, v62
	v_mul_f32_e32 v62, 0x3e0293ee, v7
	v_cmp_gt_f32_e32 vcc, s1, v62
	v_sub_f32_e32 v47, v47, v68
	v_sub_f32_e32 v20, v20, v68
	v_cndmask_b32_e32 v62, 0, v207, vcc
	v_fmac_f32_e32 v62, 0x3e0293ee, v7
	v_exp_f32_e32 v7, v62
	v_cndmask_b32_e32 v62, 0, v208, vcc
	v_sub_f32_e32 v48, v48, v68
	v_sub_f32_e32 v21, v21, v68
	v_ldexp_f32 v7, v7, v62
	v_mul_f32_e32 v62, 0x3e0293ee, v59
	v_cmp_gt_f32_e32 vcc, s1, v62
	v_sub_f32_e32 v49, v49, v68
	v_sub_f32_e32 v22, v22, v68
	v_cndmask_b32_e32 v62, 0, v207, vcc
	v_fmac_f32_e32 v62, 0x3e0293ee, v59
	v_exp_f32_e32 v59, v62
	v_cndmask_b32_e32 v62, 0, v208, vcc
	v_sub_f32_e32 v42, v42, v68
	v_sub_f32_e32 v23, v23, v68
	v_ldexp_f32 v59, v59, v62
	v_mul_f32_e32 v62, 0x3e0293ee, v8
	v_cmp_gt_f32_e32 vcc, s1, v62
	v_sub_f32_e32 v43, v43, v68
	v_sub_f32_e32 v24, v24, v68
	v_cndmask_b32_e32 v62, 0, v207, vcc
	v_fmac_f32_e32 v62, 0x3e0293ee, v8
	v_exp_f32_e32 v8, v62
	v_cndmask_b32_e32 v62, 0, v208, vcc
	v_sub_f32_e32 v44, v44, v68
	v_sub_f32_e32 v25, v25, v68
	v_ldexp_f32 v8, v8, v62
	v_mul_f32_e32 v62, 0x3e0293ee, v60
	v_cmp_gt_f32_e32 vcc, s1, v62
	v_sub_f32_e32 v45, v45, v68
	v_sub_f32_e32 v26, v26, v68
	v_cndmask_b32_e32 v62, 0, v207, vcc
	v_fmac_f32_e32 v62, 0x3e0293ee, v60
	v_exp_f32_e32 v60, v62
	v_cndmask_b32_e32 v62, 0, v208, vcc
	v_sub_f32_e32 v38, v38, v68
	v_sub_f32_e32 v27, v27, v68
	v_ldexp_f32 v60, v60, v62
	v_mul_f32_e32 v62, 0x3e0293ee, v9
	v_cmp_gt_f32_e32 vcc, s1, v62
	v_sub_f32_e32 v39, v39, v68
	v_sub_f32_e32 v28, v28, v68
	v_cndmask_b32_e32 v62, 0, v207, vcc
	v_fmac_f32_e32 v62, 0x3e0293ee, v9
	v_exp_f32_e32 v9, v62
	v_cndmask_b32_e32 v62, 0, v208, vcc
	v_sub_f32_e32 v40, v40, v68
	v_sub_f32_e32 v29, v29, v68
	v_ldexp_f32 v9, v9, v62
	v_mul_f32_e32 v62, 0x3e0293ee, v61
	v_cmp_gt_f32_e32 vcc, s1, v62
	v_add_f32_e32 v63, v8, v9
	v_bfe_u32 v65, v9, 16, 1
	v_cndmask_b32_e32 v62, 0, v207, vcc
	v_fmac_f32_e32 v62, 0x3e0293ee, v61
	v_exp_f32_e32 v61, v62
	v_cndmask_b32_e32 v62, 0, v208, vcc
	v_sub_f32_e32 v41, v41, v68
	v_sub_f32_e32 v30, v30, v68
	v_ldexp_f32 v61, v61, v62
	v_add_f32_e32 v62, v6, v7
	v_add_f32_e32 v62, v62, v63
	v_add_f32_e32 v63, v58, v59
	v_add_f32_e32 v64, v60, v61
	v_add_f32_e32 v63, v63, v64
	v_add_f32_e32 v62, v62, v63
	v_add_f32_e32 v62, v69, v62
	v_bfe_u32 v63, v61, 16, 1
	v_bfe_u32 v64, v59, 16, 1
	v_bfe_u32 v69, v7, 16, 1
	v_add3_u32 v69, v7, v69, s60
	v_add3_u32 v7, v9, v65, s60
	v_add3_u32 v59, v59, v64, s60
	v_add3_u32 v9, v61, v63, s60
	v_bfe_u32 v63, v8, 16, 1
	v_bfe_u32 v64, v58, 16, 1
	v_bfe_u32 v65, v60, 16, 1
	v_bfe_u32 v61, v6, 16, 1
	v_add3_u32 v60, v60, v65, s60
	v_add3_u32 v58, v58, v64, s60
	v_add3_u32 v8, v8, v63, s60
	v_add3_u32 v6, v6, v61, s60
	v_lshrrev_b32_e32 v61, 16, v8
	v_lshrrev_b32_e32 v8, 16, v58
	v_lshrrev_b32_e32 v58, 16, v60
	v_and_or_b32 v9, v9, s33, v58
	v_mul_f32_e32 v58, 0x3e0293ee, v10
	v_cmp_gt_f32_e32 vcc, s1, v58
	v_and_or_b32 v8, v59, s33, v8
	v_and_or_b32 v7, v7, s33, v61
	v_cndmask_b32_e32 v58, 0, v207, vcc
	v_fmac_f32_e32 v58, 0x3e0293ee, v10
	v_exp_f32_e32 v10, v58
	v_cndmask_b32_e32 v58, 0, v208, vcc
	v_sub_f32_e32 v34, v34, v68
	v_sub_f32_e32 v31, v31, v68
	v_ldexp_f32 v10, v10, v58
	v_mul_f32_e32 v58, 0x3e0293ee, v54
	v_cmp_gt_f32_e32 vcc, s1, v58
	v_sub_f32_e32 v35, v35, v68
	v_sub_f32_e32 v32, v32, v68
	v_cndmask_b32_e32 v58, 0, v207, vcc
	v_fmac_f32_e32 v58, 0x3e0293ee, v54
	v_exp_f32_e32 v54, v58
	v_cndmask_b32_e32 v58, 0, v208, vcc
	v_sub_f32_e32 v36, v36, v68
	v_sub_f32_e32 v33, v33, v68
	v_ldexp_f32 v54, v54, v58
	v_mul_f32_e32 v58, 0x3e0293ee, v11
	v_cmp_gt_f32_e32 vcc, s1, v58
	v_sub_f32_e32 v37, v37, v68
	v_lshrrev_b32_e32 v2, 16, v2
	v_cndmask_b32_e32 v58, 0, v207, vcc
	v_fmac_f32_e32 v58, 0x3e0293ee, v11
	v_exp_f32_e32 v11, v58
	v_cndmask_b32_e32 v58, 0, v208, vcc
	v_and_or_b32 v2, v73, s33, v2
	v_lshrrev_b32_e32 v6, 16, v6
	v_ldexp_f32 v11, v11, v58
	v_mul_f32_e32 v58, 0x3e0293ee, v55
	v_cmp_gt_f32_e32 vcc, s1, v58
	v_and_or_b32 v6, v69, s33, v6
	s_nop 0
	v_cndmask_b32_e32 v58, 0, v207, vcc
	v_fmac_f32_e32 v58, 0x3e0293ee, v55
	v_exp_f32_e32 v55, v58
	v_cndmask_b32_e32 v58, 0, v208, vcc
	v_ldexp_f32 v55, v55, v58
	v_mul_f32_e32 v58, 0x3e0293ee, v12
	v_cmp_gt_f32_e32 vcc, s1, v58
	s_nop 1
	v_cndmask_b32_e32 v58, 0, v207, vcc
	v_fmac_f32_e32 v58, 0x3e0293ee, v12
	v_exp_f32_e32 v12, v58
	v_cndmask_b32_e32 v58, 0, v208, vcc
	v_ldexp_f32 v12, v12, v58
	v_mul_f32_e32 v58, 0x3e0293ee, v56
	v_cmp_gt_f32_e32 vcc, s1, v58
	s_nop 1
	v_cndmask_b32_e32 v58, 0, v207, vcc
	v_fmac_f32_e32 v58, 0x3e0293ee, v56
	v_exp_f32_e32 v56, v58
	v_cndmask_b32_e32 v58, 0, v208, vcc
	v_ldexp_f32 v56, v56, v58
	v_mul_f32_e32 v58, 0x3e0293ee, v13
	v_cmp_gt_f32_e32 vcc, s1, v58
	s_nop 1
	v_cndmask_b32_e32 v58, 0, v207, vcc
	v_fmac_f32_e32 v58, 0x3e0293ee, v13
	v_exp_f32_e32 v13, v58
	v_cndmask_b32_e32 v58, 0, v208, vcc
	v_ldexp_f32 v13, v13, v58
	v_mul_f32_e32 v58, 0x3e0293ee, v57
	v_cmp_gt_f32_e32 vcc, s1, v58
	v_add_f32_e32 v59, v12, v13
	v_bfe_u32 v61, v13, 16, 1
	v_cndmask_b32_e32 v58, 0, v207, vcc
	v_fmac_f32_e32 v58, 0x3e0293ee, v57
	v_exp_f32_e32 v57, v58
	v_cndmask_b32_e32 v58, 0, v208, vcc
	v_ldexp_f32 v57, v57, v58
	v_add_f32_e32 v58, v10, v11
	v_add_f32_e32 v58, v58, v59
	v_add_f32_e32 v59, v54, v55
	v_add_f32_e32 v60, v56, v57
	v_add_f32_e32 v59, v59, v60
	v_add_f32_e32 v58, v58, v59
	v_add_f32_e32 v58, v58, v62
	v_bfe_u32 v59, v57, 16, 1
	v_bfe_u32 v60, v55, 16, 1
	v_bfe_u32 v62, v11, 16, 1
	v_add3_u32 v62, v11, v62, s60
	v_add3_u32 v11, v13, v61, s60
	v_add3_u32 v55, v55, v60, s60
	v_add3_u32 v13, v57, v59, s60
	v_bfe_u32 v59, v12, 16, 1
	v_bfe_u32 v60, v54, 16, 1
	v_bfe_u32 v61, v56, 16, 1
	v_bfe_u32 v57, v10, 16, 1
	v_add3_u32 v56, v56, v61, s60
	v_add3_u32 v54, v54, v60, s60
	v_add3_u32 v12, v12, v59, s60
	v_add3_u32 v10, v10, v57, s60
	v_lshrrev_b32_e32 v57, 16, v12
	v_lshrrev_b32_e32 v12, 16, v54
	v_lshrrev_b32_e32 v54, 16, v56
	v_and_or_b32 v13, v13, s33, v54
	v_mul_f32_e32 v54, 0x3e0293ee, v14
	v_cmp_gt_f32_e32 vcc, s1, v54
	v_and_or_b32 v12, v55, s33, v12
	v_and_or_b32 v11, v11, s33, v57
	v_cndmask_b32_e32 v54, 0, v207, vcc
	v_fmac_f32_e32 v54, 0x3e0293ee, v14
	v_exp_f32_e32 v14, v54
	v_cndmask_b32_e32 v54, 0, v208, vcc
	v_lshrrev_b32_e32 v10, 16, v10
	v_and_or_b32 v10, v62, s33, v10
	v_ldexp_f32 v14, v14, v54
	v_mul_f32_e32 v54, 0x3e0293ee, v50
	v_cmp_gt_f32_e32 vcc, s1, v54
	s_nop 1
	v_cndmask_b32_e32 v54, 0, v207, vcc
	v_fmac_f32_e32 v54, 0x3e0293ee, v50
	v_exp_f32_e32 v50, v54
	v_cndmask_b32_e32 v54, 0, v208, vcc
	v_ldexp_f32 v50, v50, v54
	v_mul_f32_e32 v54, 0x3e0293ee, v15
	v_cmp_gt_f32_e32 vcc, s1, v54
	s_nop 1
	v_cndmask_b32_e32 v54, 0, v207, vcc
	v_fmac_f32_e32 v54, 0x3e0293ee, v15
	v_exp_f32_e32 v15, v54
	v_cndmask_b32_e32 v54, 0, v208, vcc
	v_ldexp_f32 v15, v15, v54
	v_mul_f32_e32 v54, 0x3e0293ee, v51
	v_cmp_gt_f32_e32 vcc, s1, v54
	s_nop 1
	v_cndmask_b32_e32 v54, 0, v207, vcc
	v_fmac_f32_e32 v54, 0x3e0293ee, v51
	v_exp_f32_e32 v51, v54
	v_cndmask_b32_e32 v54, 0, v208, vcc
	v_ldexp_f32 v51, v51, v54
	v_mul_f32_e32 v54, 0x3e0293ee, v16
	v_cmp_gt_f32_e32 vcc, s1, v54
	s_nop 1
	v_cndmask_b32_e32 v54, 0, v207, vcc
	v_fmac_f32_e32 v54, 0x3e0293ee, v16
	v_exp_f32_e32 v16, v54
	v_cndmask_b32_e32 v54, 0, v208, vcc
	v_ldexp_f32 v16, v16, v54
	v_mul_f32_e32 v54, 0x3e0293ee, v52
	v_cmp_gt_f32_e32 vcc, s1, v54
	s_nop 1
	v_cndmask_b32_e32 v54, 0, v207, vcc
	v_fmac_f32_e32 v54, 0x3e0293ee, v52
	v_exp_f32_e32 v52, v54
	v_cndmask_b32_e32 v54, 0, v208, vcc
	v_ldexp_f32 v52, v52, v54
	v_mul_f32_e32 v54, 0x3e0293ee, v17
	v_cmp_gt_f32_e32 vcc, s1, v54
	s_nop 1
	v_cndmask_b32_e32 v54, 0, v207, vcc
	v_fmac_f32_e32 v54, 0x3e0293ee, v17
	v_exp_f32_e32 v17, v54
	v_cndmask_b32_e32 v54, 0, v208, vcc
	v_ldexp_f32 v17, v17, v54
	v_mul_f32_e32 v54, 0x3e0293ee, v53
	v_cmp_gt_f32_e32 vcc, s1, v54
	v_add_f32_e32 v55, v16, v17
	v_bfe_u32 v57, v17, 16, 1
	v_cndmask_b32_e32 v54, 0, v207, vcc
	v_fmac_f32_e32 v54, 0x3e0293ee, v53
	v_exp_f32_e32 v53, v54
	v_cndmask_b32_e32 v54, 0, v208, vcc
	v_ldexp_f32 v53, v53, v54
	v_add_f32_e32 v54, v14, v15
	v_add_f32_e32 v54, v54, v55
	v_add_f32_e32 v55, v50, v51
	v_add_f32_e32 v56, v52, v53
	v_add_f32_e32 v55, v55, v56
	v_add_f32_e32 v54, v54, v55
	v_add_f32_e32 v54, v54, v58
	v_bfe_u32 v55, v53, 16, 1
	v_bfe_u32 v56, v51, 16, 1
	v_bfe_u32 v58, v15, 16, 1
	v_add3_u32 v58, v15, v58, s60
	v_add3_u32 v15, v17, v57, s60
	v_add3_u32 v51, v51, v56, s60
	v_add3_u32 v17, v53, v55, s60
	v_bfe_u32 v55, v16, 16, 1
	v_bfe_u32 v56, v50, 16, 1
	v_bfe_u32 v57, v52, 16, 1
	v_bfe_u32 v53, v14, 16, 1
	v_add3_u32 v52, v52, v57, s60
	v_add3_u32 v50, v50, v56, s60
	v_add3_u32 v16, v16, v55, s60
	v_add3_u32 v14, v14, v53, s60
	v_lshrrev_b32_e32 v53, 16, v16
	v_lshrrev_b32_e32 v16, 16, v50
	v_lshrrev_b32_e32 v50, 16, v52
	v_and_or_b32 v17, v17, s33, v50
	v_mul_f32_e32 v50, 0x3e0293ee, v18
	v_cmp_gt_f32_e32 vcc, s1, v50
	v_and_or_b32 v16, v51, s33, v16
	v_and_or_b32 v15, v15, s33, v53
	v_cndmask_b32_e32 v50, 0, v207, vcc
	v_fmac_f32_e32 v50, 0x3e0293ee, v18
	v_exp_f32_e32 v18, v50
	v_cndmask_b32_e32 v50, 0, v208, vcc
	v_lshrrev_b32_e32 v14, 16, v14
	v_and_or_b32 v14, v58, s33, v14
	v_ldexp_f32 v18, v18, v50
	v_mul_f32_e32 v50, 0x3e0293ee, v46
	v_cmp_gt_f32_e32 vcc, s1, v50
	s_nop 1
	v_cndmask_b32_e32 v50, 0, v207, vcc
	v_fmac_f32_e32 v50, 0x3e0293ee, v46
	v_exp_f32_e32 v46, v50
	v_cndmask_b32_e32 v50, 0, v208, vcc
	v_ldexp_f32 v46, v46, v50
	v_mul_f32_e32 v50, 0x3e0293ee, v19
	v_cmp_gt_f32_e32 vcc, s1, v50
	s_nop 1
	v_cndmask_b32_e32 v50, 0, v207, vcc
	v_fmac_f32_e32 v50, 0x3e0293ee, v19
	v_exp_f32_e32 v19, v50
	v_cndmask_b32_e32 v50, 0, v208, vcc
	v_ldexp_f32 v19, v19, v50
	v_mul_f32_e32 v50, 0x3e0293ee, v47
	v_cmp_gt_f32_e32 vcc, s1, v50
	s_nop 1
	v_cndmask_b32_e32 v50, 0, v207, vcc
	v_fmac_f32_e32 v50, 0x3e0293ee, v47
	v_exp_f32_e32 v47, v50
	v_cndmask_b32_e32 v50, 0, v208, vcc
	v_ldexp_f32 v47, v47, v50
	v_mul_f32_e32 v50, 0x3e0293ee, v20
	v_cmp_gt_f32_e32 vcc, s1, v50
	s_nop 1
	v_cndmask_b32_e32 v50, 0, v207, vcc
	v_fmac_f32_e32 v50, 0x3e0293ee, v20
	v_exp_f32_e32 v20, v50
	v_cndmask_b32_e32 v50, 0, v208, vcc
	v_ldexp_f32 v20, v20, v50
	v_mul_f32_e32 v50, 0x3e0293ee, v48
	v_cmp_gt_f32_e32 vcc, s1, v50
	s_nop 1
	v_cndmask_b32_e32 v50, 0, v207, vcc
	v_fmac_f32_e32 v50, 0x3e0293ee, v48
	v_exp_f32_e32 v48, v50
	v_cndmask_b32_e32 v50, 0, v208, vcc
	v_ldexp_f32 v48, v48, v50
	v_mul_f32_e32 v50, 0x3e0293ee, v21
	v_cmp_gt_f32_e32 vcc, s1, v50
	s_nop 1
	v_cndmask_b32_e32 v50, 0, v207, vcc
	v_fmac_f32_e32 v50, 0x3e0293ee, v21
	v_exp_f32_e32 v21, v50
	v_cndmask_b32_e32 v50, 0, v208, vcc
	v_ldexp_f32 v21, v21, v50
	v_mul_f32_e32 v50, 0x3e0293ee, v49
	v_cmp_gt_f32_e32 vcc, s1, v50
	v_add_f32_e32 v51, v20, v21
	v_bfe_u32 v53, v21, 16, 1
	v_cndmask_b32_e32 v50, 0, v207, vcc
	v_fmac_f32_e32 v50, 0x3e0293ee, v49
	v_exp_f32_e32 v49, v50
	v_cndmask_b32_e32 v50, 0, v208, vcc
	v_ldexp_f32 v49, v49, v50
	v_add_f32_e32 v50, v18, v19
	v_add_f32_e32 v50, v50, v51
	v_add_f32_e32 v51, v46, v47
	v_add_f32_e32 v52, v48, v49
	v_add_f32_e32 v51, v51, v52
	v_add_f32_e32 v50, v50, v51
	v_add_f32_e32 v50, v50, v54
	v_bfe_u32 v51, v49, 16, 1
	v_bfe_u32 v52, v47, 16, 1
	v_bfe_u32 v54, v19, 16, 1
	v_add3_u32 v54, v19, v54, s60
	v_add3_u32 v19, v21, v53, s60
	v_add3_u32 v47, v47, v52, s60
	v_add3_u32 v21, v49, v51, s60
	v_bfe_u32 v51, v20, 16, 1
	v_bfe_u32 v52, v46, 16, 1
	v_bfe_u32 v53, v48, 16, 1
	v_bfe_u32 v49, v18, 16, 1
	v_add3_u32 v48, v48, v53, s60
	v_add3_u32 v46, v46, v52, s60
	v_add3_u32 v20, v20, v51, s60
	v_add3_u32 v18, v18, v49, s60
	v_lshrrev_b32_e32 v49, 16, v20
	v_lshrrev_b32_e32 v20, 16, v46
	v_lshrrev_b32_e32 v46, 16, v48
	v_and_or_b32 v21, v21, s33, v46
	v_mul_f32_e32 v46, 0x3e0293ee, v22
	v_cmp_gt_f32_e32 vcc, s1, v46
	v_and_or_b32 v20, v47, s33, v20
	v_and_or_b32 v19, v19, s33, v49
	v_cndmask_b32_e32 v46, 0, v207, vcc
	v_fmac_f32_e32 v46, 0x3e0293ee, v22
	v_exp_f32_e32 v22, v46
	v_cndmask_b32_e32 v46, 0, v208, vcc
	v_lshrrev_b32_e32 v18, 16, v18
	v_and_or_b32 v18, v54, s33, v18
	v_ldexp_f32 v22, v22, v46
	v_mul_f32_e32 v46, 0x3e0293ee, v42
	v_cmp_gt_f32_e32 vcc, s1, v46
	s_nop 1
	v_cndmask_b32_e32 v46, 0, v207, vcc
	v_fmac_f32_e32 v46, 0x3e0293ee, v42
	v_exp_f32_e32 v42, v46
	v_cndmask_b32_e32 v46, 0, v208, vcc
	v_ldexp_f32 v42, v42, v46
	v_mul_f32_e32 v46, 0x3e0293ee, v23
	v_cmp_gt_f32_e32 vcc, s1, v46
	s_nop 1
	v_cndmask_b32_e32 v46, 0, v207, vcc
	v_fmac_f32_e32 v46, 0x3e0293ee, v23
	v_exp_f32_e32 v23, v46
	v_cndmask_b32_e32 v46, 0, v208, vcc
	v_ldexp_f32 v23, v23, v46
	v_mul_f32_e32 v46, 0x3e0293ee, v43
	v_cmp_gt_f32_e32 vcc, s1, v46
	s_nop 1
	v_cndmask_b32_e32 v46, 0, v207, vcc
	v_fmac_f32_e32 v46, 0x3e0293ee, v43
	v_exp_f32_e32 v43, v46
	v_cndmask_b32_e32 v46, 0, v208, vcc
	v_ldexp_f32 v43, v43, v46
	v_mul_f32_e32 v46, 0x3e0293ee, v24
	v_cmp_gt_f32_e32 vcc, s1, v46
	s_nop 1
	v_cndmask_b32_e32 v46, 0, v207, vcc
	v_fmac_f32_e32 v46, 0x3e0293ee, v24
	v_exp_f32_e32 v24, v46
	v_cndmask_b32_e32 v46, 0, v208, vcc
	v_ldexp_f32 v24, v24, v46
	v_mul_f32_e32 v46, 0x3e0293ee, v44
	v_cmp_gt_f32_e32 vcc, s1, v46
	s_nop 1
	v_cndmask_b32_e32 v46, 0, v207, vcc
	v_fmac_f32_e32 v46, 0x3e0293ee, v44
	v_exp_f32_e32 v44, v46
	v_cndmask_b32_e32 v46, 0, v208, vcc
	v_ldexp_f32 v44, v44, v46
	v_mul_f32_e32 v46, 0x3e0293ee, v25
	v_cmp_gt_f32_e32 vcc, s1, v46
	s_nop 1
	v_cndmask_b32_e32 v46, 0, v207, vcc
	v_fmac_f32_e32 v46, 0x3e0293ee, v25
	v_exp_f32_e32 v25, v46
	v_cndmask_b32_e32 v46, 0, v208, vcc
	v_ldexp_f32 v25, v25, v46
	v_mul_f32_e32 v46, 0x3e0293ee, v45
	v_cmp_gt_f32_e32 vcc, s1, v46
	v_add_f32_e32 v47, v24, v25
	v_bfe_u32 v49, v25, 16, 1
	v_cndmask_b32_e32 v46, 0, v207, vcc
	v_fmac_f32_e32 v46, 0x3e0293ee, v45
	v_exp_f32_e32 v45, v46
	v_cndmask_b32_e32 v46, 0, v208, vcc
	v_ldexp_f32 v45, v45, v46
	v_add_f32_e32 v46, v22, v23
	v_add_f32_e32 v46, v46, v47
	v_add_f32_e32 v47, v42, v43
	v_add_f32_e32 v48, v44, v45
	v_add_f32_e32 v47, v47, v48
	v_add_f32_e32 v46, v46, v47
	v_add_f32_e32 v46, v46, v50
	v_bfe_u32 v47, v45, 16, 1
	v_bfe_u32 v48, v43, 16, 1
	v_bfe_u32 v50, v23, 16, 1
	v_add3_u32 v50, v23, v50, s60
	v_add3_u32 v23, v25, v49, s60
	v_add3_u32 v43, v43, v48, s60
	v_add3_u32 v25, v45, v47, s60
	v_bfe_u32 v47, v24, 16, 1
	v_bfe_u32 v48, v42, 16, 1
	v_bfe_u32 v49, v44, 16, 1
	v_bfe_u32 v45, v22, 16, 1
	v_add3_u32 v44, v44, v49, s60
	v_add3_u32 v42, v42, v48, s60
	v_add3_u32 v24, v24, v47, s60
	v_add3_u32 v22, v22, v45, s60
	v_lshrrev_b32_e32 v45, 16, v24
	v_lshrrev_b32_e32 v24, 16, v42
	v_lshrrev_b32_e32 v42, 16, v44
	v_and_or_b32 v25, v25, s33, v42
	v_mul_f32_e32 v42, 0x3e0293ee, v26
	v_cmp_gt_f32_e32 vcc, s1, v42
	v_and_or_b32 v24, v43, s33, v24
	v_and_or_b32 v23, v23, s33, v45
	v_cndmask_b32_e32 v42, 0, v207, vcc
	v_fmac_f32_e32 v42, 0x3e0293ee, v26
	v_exp_f32_e32 v26, v42
	v_cndmask_b32_e32 v42, 0, v208, vcc
	v_lshrrev_b32_e32 v22, 16, v22
	v_and_or_b32 v22, v50, s33, v22
	v_ldexp_f32 v26, v26, v42
	v_mul_f32_e32 v42, 0x3e0293ee, v38
	v_cmp_gt_f32_e32 vcc, s1, v42
	s_nop 1
	v_cndmask_b32_e32 v42, 0, v207, vcc
	v_fmac_f32_e32 v42, 0x3e0293ee, v38
	v_exp_f32_e32 v38, v42
	v_cndmask_b32_e32 v42, 0, v208, vcc
	v_ldexp_f32 v38, v38, v42
	v_mul_f32_e32 v42, 0x3e0293ee, v27
	v_cmp_gt_f32_e32 vcc, s1, v42
	s_nop 1
	v_cndmask_b32_e32 v42, 0, v207, vcc
	v_fmac_f32_e32 v42, 0x3e0293ee, v27
	v_exp_f32_e32 v27, v42
	v_cndmask_b32_e32 v42, 0, v208, vcc
	v_ldexp_f32 v27, v27, v42
	v_mul_f32_e32 v42, 0x3e0293ee, v39
	v_cmp_gt_f32_e32 vcc, s1, v42
	s_nop 1
	v_cndmask_b32_e32 v42, 0, v207, vcc
	v_fmac_f32_e32 v42, 0x3e0293ee, v39
	v_exp_f32_e32 v39, v42
	v_cndmask_b32_e32 v42, 0, v208, vcc
	v_ldexp_f32 v39, v39, v42
	v_mul_f32_e32 v42, 0x3e0293ee, v28
	v_cmp_gt_f32_e32 vcc, s1, v42
	s_nop 1
	v_cndmask_b32_e32 v42, 0, v207, vcc
	v_fmac_f32_e32 v42, 0x3e0293ee, v28
	v_exp_f32_e32 v28, v42
	v_cndmask_b32_e32 v42, 0, v208, vcc
	v_ldexp_f32 v28, v28, v42
	v_mul_f32_e32 v42, 0x3e0293ee, v40
	v_cmp_gt_f32_e32 vcc, s1, v42
	s_nop 1
	v_cndmask_b32_e32 v42, 0, v207, vcc
	v_fmac_f32_e32 v42, 0x3e0293ee, v40
	v_exp_f32_e32 v40, v42
	v_cndmask_b32_e32 v42, 0, v208, vcc
	v_ldexp_f32 v40, v40, v42
	v_mul_f32_e32 v42, 0x3e0293ee, v29
	v_cmp_gt_f32_e32 vcc, s1, v42
	s_nop 1
	v_cndmask_b32_e32 v42, 0, v207, vcc
	v_fmac_f32_e32 v42, 0x3e0293ee, v29
	v_exp_f32_e32 v29, v42
	v_cndmask_b32_e32 v42, 0, v208, vcc
	v_ldexp_f32 v29, v29, v42
	v_mul_f32_e32 v42, 0x3e0293ee, v41
	v_cmp_gt_f32_e32 vcc, s1, v42
	v_add_f32_e32 v43, v28, v29
	v_bfe_u32 v45, v29, 16, 1
	v_cndmask_b32_e32 v42, 0, v207, vcc
	v_fmac_f32_e32 v42, 0x3e0293ee, v41
	v_exp_f32_e32 v41, v42
	v_cndmask_b32_e32 v42, 0, v208, vcc
	v_ldexp_f32 v41, v41, v42
	v_add_f32_e32 v42, v26, v27
	v_add_f32_e32 v42, v42, v43
	v_add_f32_e32 v43, v38, v39
	v_add_f32_e32 v44, v40, v41
	v_add_f32_e32 v43, v43, v44
	v_add_f32_e32 v42, v42, v43
	v_add_f32_e32 v42, v42, v46
	v_bfe_u32 v43, v41, 16, 1
	v_bfe_u32 v44, v39, 16, 1
	v_bfe_u32 v46, v27, 16, 1
	v_add3_u32 v46, v27, v46, s60
	v_add3_u32 v27, v29, v45, s60
	v_add3_u32 v39, v39, v44, s60
	v_add3_u32 v29, v41, v43, s60
	v_bfe_u32 v43, v28, 16, 1
	v_bfe_u32 v44, v38, 16, 1
	v_bfe_u32 v45, v40, 16, 1
	v_bfe_u32 v41, v26, 16, 1
	v_add3_u32 v40, v40, v45, s60
	v_add3_u32 v38, v38, v44, s60
	v_add3_u32 v28, v28, v43, s60
	v_add3_u32 v26, v26, v41, s60
	v_lshrrev_b32_e32 v41, 16, v28
	v_lshrrev_b32_e32 v28, 16, v38
	v_lshrrev_b32_e32 v38, 16, v40
	v_and_or_b32 v29, v29, s33, v38
	v_mul_f32_e32 v38, 0x3e0293ee, v30
	v_cmp_gt_f32_e32 vcc, s1, v38
	v_and_or_b32 v28, v39, s33, v28
	v_and_or_b32 v27, v27, s33, v41
	v_cndmask_b32_e32 v38, 0, v207, vcc
	v_fmac_f32_e32 v38, 0x3e0293ee, v30
	v_exp_f32_e32 v30, v38
	v_cndmask_b32_e32 v38, 0, v208, vcc
	v_lshrrev_b32_e32 v26, 16, v26
	v_and_or_b32 v26, v46, s33, v26
	v_ldexp_f32 v30, v30, v38
	v_mul_f32_e32 v38, 0x3e0293ee, v34
	v_cmp_gt_f32_e32 vcc, s1, v38
	s_nop 1
	v_cndmask_b32_e32 v38, 0, v207, vcc
	v_fmac_f32_e32 v38, 0x3e0293ee, v34
	v_exp_f32_e32 v34, v38
	v_cndmask_b32_e32 v38, 0, v208, vcc
	v_ldexp_f32 v34, v34, v38
	v_mul_f32_e32 v38, 0x3e0293ee, v31
	v_cmp_gt_f32_e32 vcc, s1, v38
	s_nop 1
	v_cndmask_b32_e32 v38, 0, v207, vcc
	v_fmac_f32_e32 v38, 0x3e0293ee, v31
	v_exp_f32_e32 v31, v38
	v_cndmask_b32_e32 v38, 0, v208, vcc
	v_ldexp_f32 v31, v31, v38
	v_mul_f32_e32 v38, 0x3e0293ee, v35
	v_cmp_gt_f32_e32 vcc, s1, v38
	s_nop 1
	v_cndmask_b32_e32 v38, 0, v207, vcc
	v_fmac_f32_e32 v38, 0x3e0293ee, v35
	v_exp_f32_e32 v35, v38
	v_cndmask_b32_e32 v38, 0, v208, vcc
	v_ldexp_f32 v35, v35, v38
	v_mul_f32_e32 v38, 0x3e0293ee, v32
	v_cmp_gt_f32_e32 vcc, s1, v38
	s_nop 1
	v_cndmask_b32_e32 v38, 0, v207, vcc
	v_fmac_f32_e32 v38, 0x3e0293ee, v32
	v_exp_f32_e32 v32, v38
	v_cndmask_b32_e32 v38, 0, v208, vcc
	v_ldexp_f32 v32, v32, v38
	v_mul_f32_e32 v38, 0x3e0293ee, v36
	v_cmp_gt_f32_e32 vcc, s1, v38
	s_nop 1
	v_cndmask_b32_e32 v38, 0, v207, vcc
	v_fmac_f32_e32 v38, 0x3e0293ee, v36
	v_exp_f32_e32 v36, v38
	v_cndmask_b32_e32 v38, 0, v208, vcc
	v_ldexp_f32 v36, v36, v38
	v_mul_f32_e32 v38, 0x3e0293ee, v33
	v_cmp_gt_f32_e32 vcc, s1, v38
	s_nop 1
	v_cndmask_b32_e32 v38, 0, v207, vcc
	v_fmac_f32_e32 v38, 0x3e0293ee, v33
	v_exp_f32_e32 v33, v38
	v_cndmask_b32_e32 v38, 0, v208, vcc
	v_ldexp_f32 v33, v33, v38
	v_mul_f32_e32 v38, 0x3e0293ee, v37
	v_cmp_gt_f32_e32 vcc, s1, v38
	v_add_f32_e32 v39, v32, v33
	v_bfe_u32 v41, v33, 16, 1
	v_cndmask_b32_e32 v38, 0, v207, vcc
	v_fmac_f32_e32 v38, 0x3e0293ee, v37
	v_exp_f32_e32 v37, v38
	v_cndmask_b32_e32 v38, 0, v208, vcc
	v_ldexp_f32 v37, v37, v38
	v_add_f32_e32 v38, v30, v31
	v_add_f32_e32 v38, v38, v39
	v_add_f32_e32 v39, v34, v35
	v_add_f32_e32 v40, v36, v37
	v_add_f32_e32 v39, v39, v40
	v_add_f32_e32 v38, v38, v39
	v_add_f32_e32 v38, v38, v42
	v_bfe_u32 v39, v37, 16, 1
	v_bfe_u32 v40, v35, 16, 1
	v_bfe_u32 v42, v31, 16, 1
	v_add3_u32 v42, v31, v42, s60
	v_add3_u32 v31, v33, v41, s60
	v_add3_u32 v35, v35, v40, s60
	v_add3_u32 v33, v37, v39, s60
	v_bfe_u32 v39, v32, 16, 1
	v_bfe_u32 v40, v34, 16, 1
	v_bfe_u32 v41, v36, 16, 1
	v_bfe_u32 v37, v30, 16, 1
	v_add3_u32 v36, v36, v41, s60
	v_add3_u32 v34, v34, v40, s60
	v_add3_u32 v32, v32, v39, s60
	v_add3_u32 v30, v30, v37, s60
	v_lshrrev_b32_e32 v37, 16, v32
	v_lshrrev_b32_e32 v32, 16, v34
	v_lshrrev_b32_e32 v34, 16, v36
	v_and_or_b32 v33, v33, s33, v34
	ds_bpermute_b32 v34, v66, v38
	v_and_or_b32 v32, v35, s33, v32
	v_and_or_b32 v31, v31, s33, v37
	v_lshrrev_b32_e32 v30, 16, v30
	v_and_or_b32 v30, v42, s33, v30
	s_waitcnt lgkmcnt(0)
	v_add_f32_e32 v34, v38, v34
	ds_bpermute_b32 v35, v67, v34
	s_waitcnt lgkmcnt(0)
	v_add_f32_e32 v34, v34, v35
	v_rcp_f32_e32 v40, v34
	v_lshlrev_b64 v[34:35], 10, v[0:1]
	v_lshl_add_u64 v[34:35], s[16:17], 0, v[34:35]
	v_lshl_add_u64 v[34:35], v[34:35], 0, s[46:47]
	v_lshlrev_b32_e32 v0, 1, v80
	v_lshl_add_u64 v[38:39], v[34:35], 0, v[0:1]
	ds_read_u16 v46, v145
	ds_read_u16 v47, v145 offset:264
	ds_read_u16 v48, v145 offset:528
	ds_read_u16 v49, v145 offset:792
	ds_read_u16 v50, v145 offset:4224
	ds_read_u16 v51, v145 offset:4488
	ds_read_u16 v52, v145 offset:4752
	ds_read_u16 v53, v145 offset:5016
	ds_read_u16 v54, v145 offset:8448
	ds_read_u16 v55, v145 offset:8712
	ds_read_u16 v56, v145 offset:8976
	ds_read_u16 v57, v145 offset:9240
	ds_read_u16 v58, v145 offset:12672
	ds_read_u16 v59, v145 offset:12936
	ds_read_u16 v60, v145 offset:13200
	s_waitcnt lgkmcnt(7)
	ds_read_u16 v61, v145 offset:13464
	v_lshl_or_b32 v62, v47, 16, v46
	v_lshl_or_b32 v63, v49, 16, v48
	v_lshl_or_b32 v64, v51, 16, v50
	v_lshl_or_b32 v65, v53, 16, v52
	s_nop 1
	v_mfma_f32_16x16x32_bf16 v[34:37], v[62:65], v[2:5], 0
	ds_read_u16 v46, v145 offset:16896
	ds_read_u16 v47, v145 offset:17160
	ds_read_u16 v48, v145 offset:17424
	ds_read_u16 v49, v145 offset:17688
	ds_read_u16 v50, v145 offset:21120
	ds_read_u16 v51, v145 offset:21384
	ds_read_u16 v52, v145 offset:21648
	s_waitcnt lgkmcnt(7)
	ds_read_u16 v53, v145 offset:21912
	v_lshl_or_b32 v42, v55, 16, v54
	v_lshl_or_b32 v43, v57, 16, v56
	v_lshl_or_b32 v44, v59, 16, v58
	v_lshl_or_b32 v45, v61, 16, v60
	s_nop 1
	v_mfma_f32_16x16x32_bf16 v[34:37], v[42:45], v[6:9], v[34:37]
	ds_read_u16 v54, v145 offset:25344
	ds_read_u16 v55, v145 offset:25608
	ds_read_u16 v56, v145 offset:25872
	ds_read_u16 v57, v145 offset:26136
	ds_read_u16 v58, v145 offset:29568
	ds_read_u16 v59, v145 offset:29832
	ds_read_u16 v60, v145 offset:30096
	s_waitcnt lgkmcnt(7)
	ds_read_u16 v61, v145 offset:30360
	v_lshl_or_b32 v62, v47, 16, v46
	v_lshl_or_b32 v63, v49, 16, v48
	v_lshl_or_b32 v64, v51, 16, v50
	v_lshl_or_b32 v65, v53, 16, v52
	s_nop 1
	v_mfma_f32_16x16x32_bf16 v[34:37], v[62:65], v[10:13], v[34:37]
	ds_read_u16 v46, v145 offset:33792
	ds_read_u16 v47, v145 offset:34056
	ds_read_u16 v48, v145 offset:34320
	ds_read_u16 v49, v145 offset:34584
	ds_read_u16 v50, v145 offset:38016
	ds_read_u16 v51, v145 offset:38280
	ds_read_u16 v52, v145 offset:38544
	s_waitcnt lgkmcnt(7)
	ds_read_u16 v53, v145 offset:38808
	v_lshl_or_b32 v42, v55, 16, v54
	v_lshl_or_b32 v43, v57, 16, v56
	v_lshl_or_b32 v44, v59, 16, v58
	v_lshl_or_b32 v45, v61, 16, v60
	s_nop 1
	v_mfma_f32_16x16x32_bf16 v[34:37], v[42:45], v[14:17], v[34:37]
	ds_read_u16 v54, v145 offset:42240
	ds_read_u16 v55, v145 offset:42504
	ds_read_u16 v56, v145 offset:42768
	ds_read_u16 v57, v145 offset:43032
	ds_read_u16 v58, v145 offset:46464
	ds_read_u16 v59, v145 offset:46728
	ds_read_u16 v60, v145 offset:46992
	s_waitcnt lgkmcnt(7)
	ds_read_u16 v61, v145 offset:47256
	v_lshl_or_b32 v62, v47, 16, v46
	v_lshl_or_b32 v63, v49, 16, v48
	v_lshl_or_b32 v64, v51, 16, v50
	v_lshl_or_b32 v65, v53, 16, v52
	s_nop 1
	v_mfma_f32_16x16x32_bf16 v[34:37], v[62:65], v[18:21], v[34:37]
	ds_read_u16 v46, v145 offset:50688
	ds_read_u16 v47, v145 offset:50952
	ds_read_u16 v48, v145 offset:51216
	ds_read_u16 v49, v145 offset:51480
	ds_read_u16 v50, v145 offset:54912
	ds_read_u16 v51, v145 offset:55176
	ds_read_u16 v52, v145 offset:55440
	s_waitcnt lgkmcnt(7)
	ds_read_u16 v53, v145 offset:55704
	v_lshl_or_b32 v42, v55, 16, v54
	v_lshl_or_b32 v43, v57, 16, v56
	v_lshl_or_b32 v44, v59, 16, v58
	v_lshl_or_b32 v45, v61, 16, v60
	s_nop 1
	v_mfma_f32_16x16x32_bf16 v[34:37], v[42:45], v[22:25], v[34:37]
	ds_read_u16 v54, v145 offset:59136
	ds_read_u16 v55, v145 offset:59400
	ds_read_u16 v56, v145 offset:59664
	ds_read_u16 v57, v145 offset:59928
	ds_read_u16 v58, v145 offset:63360
	ds_read_u16 v59, v145 offset:63624
	ds_read_u16 v60, v145 offset:63888
	s_waitcnt lgkmcnt(7)
	ds_read_u16 v61, v145 offset:64152
	v_lshl_or_b32 v62, v47, 16, v46
	v_lshl_or_b32 v63, v49, 16, v48
	v_lshl_or_b32 v64, v51, 16, v50
	v_lshl_or_b32 v65, v53, 16, v52
	s_nop 1
	v_mfma_f32_16x16x32_bf16 v[34:37], v[62:65], v[26:29], v[34:37]
	ds_read_u16 v46, v145 offset:32
	ds_read_u16 v47, v145 offset:296
	ds_read_u16 v48, v145 offset:560
	ds_read_u16 v49, v145 offset:824
	ds_read_u16 v50, v145 offset:4256
	ds_read_u16 v51, v145 offset:4520
	ds_read_u16 v52, v145 offset:4784
	s_waitcnt lgkmcnt(7)
	ds_read_u16 v53, v145 offset:5048
	v_lshl_or_b32 v42, v55, 16, v54
	v_lshl_or_b32 v43, v57, 16, v56
	v_lshl_or_b32 v44, v59, 16, v58
	v_lshl_or_b32 v45, v61, 16, v60
	s_nop 1
	v_mfma_f32_16x16x32_bf16 v[34:37], v[42:45], v[30:33], v[34:37]
	s_and_saveexec_b64 s[24:25], s[6:7]
	s_cbranch_execz .LBB0_100
	s_nop 5
	v_mov_b32_e32 v43, v36
	v_mov_b32_e32 v36, v35
	v_mov_b32_e32 v42, v34
	v_pk_mul_f32 v[34:35], v[40:41], v[36:37] op_sel_hi:[0,1]
	v_pk_mul_f32 v[42:43], v[40:41], v[42:43] op_sel_hi:[0,1]
	v_and_b32_sdwa v37, v35, v202 dst_sel:DWORD dst_unused:UNUSED_PAD src0_sel:WORD_1 src1_sel:DWORD
	v_and_b32_sdwa v41, v34, v202 dst_sel:DWORD dst_unused:UNUSED_PAD src0_sel:WORD_1 src1_sel:DWORD
	v_and_b32_sdwa v0, v43, v202 dst_sel:DWORD dst_unused:UNUSED_PAD src0_sel:WORD_1 src1_sel:DWORD
	v_and_b32_sdwa v36, v42, v202 dst_sel:DWORD dst_unused:UNUSED_PAD src0_sel:WORD_1 src1_sel:DWORD
	v_add3_u32 v35, v35, v37, s60
	v_add3_u32 v34, v34, v41, s60
	v_add3_u32 v36, v42, v36, s60
	v_add3_u32 v0, v43, v0, s60
	v_and_b32_e32 v35, 0xffff0000, v35
	v_and_b32_e32 v34, 0xffff0000, v34
	v_or_b32_sdwa v35, v35, v0 dst_sel:DWORD dst_unused:UNUSED_PAD src0_sel:DWORD src1_sel:WORD_1
	v_or_b32_sdwa v34, v34, v36 dst_sel:DWORD dst_unused:UNUSED_PAD src0_sel:DWORD src1_sel:WORD_1
	global_store_dwordx2 v[38:39], v[34:35], off

.LBB0_125:
	s_or_b64 exec, exec, s[24:25]
	s_waitcnt vmcnt(0)
	v_bfe_u32 v0, v30, 16, 1
	v_add3_u32 v0, v30, v0, s60
	v_bfe_u32 v30, v31, 16, 1
	v_lshrrev_b32_e32 v0, 16, v0
	v_add3_u32 v30, v31, v30, s60
	v_and_or_b32 v34, v30, s33, v0
	v_bfe_u32 v0, v32, 16, 1
	v_add3_u32 v0, v32, v0, s60
	v_bfe_u32 v30, v33, 16, 1
	v_lshrrev_b32_e32 v0, 16, v0
	v_add3_u32 v30, v33, v30, s60
	v_and_or_b32 v35, v30, s33, v0
	v_bfe_u32 v0, v26, 16, 1
	v_add3_u32 v0, v26, v0, s60
	v_bfe_u32 v26, v27, 16, 1
	v_lshrrev_b32_e32 v0, 16, v0
	v_add3_u32 v26, v27, v26, s60
	v_and_or_b32 v36, v26, s33, v0
	v_bfe_u32 v0, v28, 16, 1
	v_add3_u32 v0, v28, v0, s60
	v_bfe_u32 v26, v29, 16, 1
	v_lshrrev_b32_e32 v0, 16, v0
	v_add3_u32 v26, v29, v26, s60
	v_and_or_b32 v37, v26, s33, v0
	v_bfe_u32 v0, v18, 16, 1
	v_add3_u32 v0, v18, v0, s60
	v_bfe_u32 v18, v19, 16, 1
	v_lshrrev_b32_e32 v0, 16, v0
	v_add3_u32 v18, v19, v18, s60
	v_and_or_b32 v66, v18, s33, v0
	v_bfe_u32 v0, v20, 16, 1
	v_add3_u32 v0, v20, v0, s60
	v_bfe_u32 v18, v21, 16, 1
	v_lshrrev_b32_e32 v0, 16, v0
	v_add3_u32 v18, v21, v18, s60
	v_and_or_b32 v67, v18, s33, v0
	v_bfe_u32 v0, v10, 16, 1
	v_add3_u32 v0, v10, v0, s60
	v_bfe_u32 v10, v11, 16, 1
	v_lshrrev_b32_e32 v0, 16, v0
	v_add3_u32 v10, v11, v10, s60
	v_and_or_b32 v68, v10, s33, v0
	v_bfe_u32 v0, v12, 16, 1
	v_add3_u32 v0, v12, v0, s60
	v_bfe_u32 v10, v13, 16, 1
	v_lshrrev_b32_e32 v0, 16, v0
	v_add3_u32 v10, v13, v10, s60
	v_and_or_b32 v69, v10, s33, v0
	v_bfe_u32 v0, v6, 16, 1
	v_add3_u32 v0, v6, v0, s60
	v_bfe_u32 v6, v7, 16, 1
	v_lshrrev_b32_e32 v0, 16, v0
	v_add3_u32 v6, v7, v6, s60
	v_and_or_b32 v70, v6, s33, v0
	v_bfe_u32 v0, v8, 16, 1
	v_add3_u32 v0, v8, v0, s60
	v_bfe_u32 v6, v9, 16, 1
	v_lshrrev_b32_e32 v0, 16, v0
	v_add3_u32 v6, v9, v6, s60
	v_and_or_b32 v71, v6, s33, v0
	v_bfe_u32 v0, v2, 16, 1
	v_add3_u32 v0, v2, v0, s60
	v_bfe_u32 v2, v3, 16, 1
	v_lshrrev_b32_e32 v0, 16, v0
	v_add3_u32 v2, v3, v2, s60
	v_and_or_b32 v72, v2, s33, v0
	v_bfe_u32 v0, v4, 16, 1
	v_add3_u32 v0, v4, v0, s60
	v_bfe_u32 v2, v5, 16, 1
	v_lshrrev_b32_e32 v0, 16, v0
	v_add3_u32 v2, v5, v2, s60
	v_and_or_b32 v73, v2, s33, v0
	v_bfe_u32 v0, v22, 16, 1
	v_add3_u32 v0, v22, v0, s60
	v_bfe_u32 v2, v23, 16, 1
	v_lshrrev_b32_e32 v0, 16, v0
	v_add3_u32 v2, v23, v2, s60
	v_and_or_b32 v74, v2, s33, v0
	v_bfe_u32 v0, v24, 16, 1
	v_add3_u32 v0, v24, v0, s60
	v_bfe_u32 v2, v25, 16, 1
	v_lshrrev_b32_e32 v0, 16, v0
	v_add3_u32 v2, v25, v2, s60
	v_and_or_b32 v75, v2, s33, v0
	v_bfe_u32 v0, v14, 16, 1
	v_add3_u32 v0, v14, v0, s60
	v_bfe_u32 v2, v15, 16, 1
	v_lshrrev_b32_e32 v0, 16, v0
	v_add3_u32 v2, v15, v2, s60
	v_and_or_b32 v76, v2, s33, v0
	v_bfe_u32 v0, v16, 16, 1
	v_add3_u32 v0, v16, v0, s60
	v_bfe_u32 v2, v17, 16, 1
	v_lshrrev_b32_e32 v0, 16, v0
	v_add3_u32 v2, v17, v2, s60
	v_and_or_b32 v77, v2, s33, v0
	s_mov_b32 s1, 0xff61b1e6
	s_lshl_b32 s46, s0, 1
	ds_read_b128 v[180:183], v140
	ds_read_b128 v[184:187], v140 offset:64
	ds_read_b128 v[188:191], v140 offset:128
	ds_read_b128 v[192:195], v140 offset:192
	ds_read_b128 v[196:199], v140 offset:4352
	ds_read_b128 v[220:223], v140 offset:4416
	ds_read_b128 v[224:227], v140 offset:4480
	ds_read_b128 v[228:231], v140 offset:4544
	ds_read_b128 v[232:235], v140 offset:8704
	ds_read_b128 v[236:239], v140 offset:8768
	ds_read_b128 v[240:243], v140 offset:8832
	ds_read_b128 v[244:247], v140 offset:8896
	s_waitcnt lgkmcnt(11)
	v_mfma_f32_16x16x32_bf16 v[2:5], v[180:183], v[70:73], 0
	ds_read_b128 v[180:183], v140 offset:13056
	s_waitcnt lgkmcnt(11)
	v_mfma_f32_16x16x32_bf16 v[2:5], v[184:187], v[66:69], v[2:5]
	ds_read_b128 v[184:187], v140 offset:13120
	s_waitcnt lgkmcnt(11)
	v_mfma_f32_16x16x32_bf16 v[2:5], v[188:191], v[34:37], v[2:5]
	ds_read_b128 v[188:191], v140 offset:13184
	s_waitcnt lgkmcnt(11)
	v_mfma_f32_16x16x32_bf16 v[2:5], v[192:195], v[74:77], v[2:5]
	ds_read_b128 v[192:195], v140 offset:13248
	s_waitcnt lgkmcnt(11)
	v_mfma_f32_16x16x32_bf16 v[62:65], v[196:199], v[70:73], 0
	ds_read_b128 v[196:199], v140 offset:17408
	s_waitcnt lgkmcnt(11)
	v_mfma_f32_16x16x32_bf16 v[62:65], v[220:223], v[66:69], v[62:65]
	ds_read_b128 v[220:223], v140 offset:17472
	s_waitcnt lgkmcnt(11)
	v_mfma_f32_16x16x32_bf16 v[62:65], v[224:227], v[34:37], v[62:65]
	ds_read_b128 v[224:227], v140 offset:17536
	s_waitcnt lgkmcnt(11)
	v_mfma_f32_16x16x32_bf16 v[62:65], v[228:231], v[74:77], v[62:65]
	ds_read_b128 v[228:231], v140 offset:17600
	s_waitcnt lgkmcnt(11)
	v_mfma_f32_16x16x32_bf16 v[6:9], v[232:235], v[70:73], 0
	ds_read_b128 v[232:235], v140 offset:21760
	s_waitcnt lgkmcnt(11)
	v_mfma_f32_16x16x32_bf16 v[6:9], v[236:239], v[66:69], v[6:9]
	ds_read_b128 v[236:239], v140 offset:21824
	s_waitcnt lgkmcnt(11)
	v_mfma_f32_16x16x32_bf16 v[6:9], v[240:243], v[34:37], v[6:9]
	ds_read_b128 v[240:243], v140 offset:21888
	s_waitcnt lgkmcnt(11)
	v_mfma_f32_16x16x32_bf16 v[6:9], v[244:247], v[74:77], v[6:9]
	ds_read_b128 v[244:247], v140 offset:21952
	s_waitcnt lgkmcnt(11)
	v_mfma_f32_16x16x32_bf16 v[58:61], v[180:183], v[70:73], 0
	ds_read_b128 v[180:183], v140 offset:26112
	s_waitcnt lgkmcnt(11)
	v_mfma_f32_16x16x32_bf16 v[58:61], v[184:187], v[66:69], v[58:61]
	ds_read_b128 v[184:187], v140 offset:26176
	s_waitcnt lgkmcnt(11)
	v_mfma_f32_16x16x32_bf16 v[58:61], v[188:191], v[34:37], v[58:61]
	ds_read_b128 v[188:191], v140 offset:26240
	s_waitcnt lgkmcnt(11)
	v_mfma_f32_16x16x32_bf16 v[58:61], v[192:195], v[74:77], v[58:61]
	ds_read_b128 v[192:195], v140 offset:26304
	s_waitcnt lgkmcnt(11)
	v_mfma_f32_16x16x32_bf16 v[10:13], v[196:199], v[70:73], 0
	ds_read_b128 v[196:199], v140 offset:30464
	s_waitcnt lgkmcnt(11)
	v_mfma_f32_16x16x32_bf16 v[10:13], v[220:223], v[66:69], v[10:13]
	ds_read_b128 v[220:223], v140 offset:30528
	s_waitcnt lgkmcnt(11)
	v_mfma_f32_16x16x32_bf16 v[10:13], v[224:227], v[34:37], v[10:13]
	ds_read_b128 v[224:227], v140 offset:30592
	s_waitcnt lgkmcnt(11)
	v_mfma_f32_16x16x32_bf16 v[10:13], v[228:231], v[74:77], v[10:13]
	ds_read_b128 v[228:231], v140 offset:30656
	s_waitcnt lgkmcnt(11)
	v_mfma_f32_16x16x32_bf16 v[54:57], v[232:235], v[70:73], 0
	ds_read_b128 v[232:235], v140 offset:34816
	s_waitcnt lgkmcnt(11)
	v_mfma_f32_16x16x32_bf16 v[54:57], v[236:239], v[66:69], v[54:57]
	ds_read_b128 v[236:239], v140 offset:34880
	s_waitcnt lgkmcnt(11)
	v_mfma_f32_16x16x32_bf16 v[54:57], v[240:243], v[34:37], v[54:57]
	ds_read_b128 v[240:243], v140 offset:34944
	s_waitcnt lgkmcnt(11)
	v_mfma_f32_16x16x32_bf16 v[54:57], v[244:247], v[74:77], v[54:57]
	ds_read_b128 v[244:247], v140 offset:35008
	s_waitcnt lgkmcnt(11)
	v_mfma_f32_16x16x32_bf16 v[14:17], v[180:183], v[70:73], 0
	ds_read_b128 v[180:183], v140 offset:39168
	s_waitcnt lgkmcnt(11)
	v_mfma_f32_16x16x32_bf16 v[14:17], v[184:187], v[66:69], v[14:17]
	ds_read_b128 v[184:187], v140 offset:39232
	s_waitcnt lgkmcnt(11)
	v_mfma_f32_16x16x32_bf16 v[14:17], v[188:191], v[34:37], v[14:17]
	ds_read_b128 v[188:191], v140 offset:39296
	s_waitcnt lgkmcnt(11)
	v_mfma_f32_16x16x32_bf16 v[14:17], v[192:195], v[74:77], v[14:17]
	ds_read_b128 v[192:195], v140 offset:39360
	s_waitcnt lgkmcnt(11)
	v_mfma_f32_16x16x32_bf16 v[50:53], v[196:199], v[70:73], 0
	ds_read_b128 v[196:199], v140 offset:43520
	s_waitcnt lgkmcnt(11)
	v_mfma_f32_16x16x32_bf16 v[50:53], v[220:223], v[66:69], v[50:53]
	ds_read_b128 v[220:223], v140 offset:43584
	s_waitcnt lgkmcnt(11)
	v_mfma_f32_16x16x32_bf16 v[50:53], v[224:227], v[34:37], v[50:53]
	ds_read_b128 v[224:227], v140 offset:43648
	s_waitcnt lgkmcnt(11)
	v_mfma_f32_16x16x32_bf16 v[50:53], v[228:231], v[74:77], v[50:53]
	ds_read_b128 v[228:231], v140 offset:43712
	s_waitcnt lgkmcnt(11)
	v_mfma_f32_16x16x32_bf16 v[18:21], v[232:235], v[70:73], 0
	ds_read_b128 v[232:235], v140 offset:47872
	s_waitcnt lgkmcnt(11)
	v_mfma_f32_16x16x32_bf16 v[18:21], v[236:239], v[66:69], v[18:21]
	ds_read_b128 v[236:239], v140 offset:47936
	s_waitcnt lgkmcnt(11)
	v_mfma_f32_16x16x32_bf16 v[18:21], v[240:243], v[34:37], v[18:21]
	ds_read_b128 v[240:243], v140 offset:48000
	s_waitcnt lgkmcnt(11)
	v_mfma_f32_16x16x32_bf16 v[18:21], v[244:247], v[74:77], v[18:21]
	ds_read_b128 v[244:247], v140 offset:48064
	s_waitcnt lgkmcnt(11)
	v_mfma_f32_16x16x32_bf16 v[46:49], v[180:183], v[70:73], 0
	ds_read_b128 v[180:183], v140 offset:52224
	s_waitcnt lgkmcnt(11)
	v_mfma_f32_16x16x32_bf16 v[46:49], v[184:187], v[66:69], v[46:49]
	ds_read_b128 v[184:187], v140 offset:52288
	s_waitcnt lgkmcnt(11)
	v_mfma_f32_16x16x32_bf16 v[46:49], v[188:191], v[34:37], v[46:49]
	ds_read_b128 v[188:191], v140 offset:52352
	s_waitcnt lgkmcnt(11)
	v_mfma_f32_16x16x32_bf16 v[46:49], v[192:195], v[74:77], v[46:49]
	ds_read_b128 v[192:195], v140 offset:52416
	s_waitcnt lgkmcnt(11)
	v_mfma_f32_16x16x32_bf16 v[22:25], v[196:199], v[70:73], 0
	ds_read_b128 v[196:199], v140 offset:56576
	s_waitcnt lgkmcnt(11)
	v_mfma_f32_16x16x32_bf16 v[22:25], v[220:223], v[66:69], v[22:25]
	ds_read_b128 v[220:223], v140 offset:56640
	s_waitcnt lgkmcnt(11)
	v_mfma_f32_16x16x32_bf16 v[22:25], v[224:227], v[34:37], v[22:25]
	ds_read_b128 v[224:227], v140 offset:56704
	s_waitcnt lgkmcnt(11)
	v_mfma_f32_16x16x32_bf16 v[22:25], v[228:231], v[74:77], v[22:25]
	ds_read_b128 v[228:231], v140 offset:56768
	s_waitcnt lgkmcnt(11)
	v_mfma_f32_16x16x32_bf16 v[42:45], v[232:235], v[70:73], 0
	ds_read_b128 v[232:235], v140 offset:60928
	s_waitcnt lgkmcnt(11)
	v_mfma_f32_16x16x32_bf16 v[42:45], v[236:239], v[66:69], v[42:45]
	ds_read_b128 v[236:239], v140 offset:60992
	s_waitcnt lgkmcnt(11)
	v_mfma_f32_16x16x32_bf16 v[42:45], v[240:243], v[34:37], v[42:45]
	ds_read_b128 v[240:243], v140 offset:61056
	s_waitcnt lgkmcnt(11)
	v_mfma_f32_16x16x32_bf16 v[42:45], v[244:247], v[74:77], v[42:45]
	ds_read_b128 v[244:247], v140 offset:61120
	s_waitcnt lgkmcnt(11)
	v_mfma_f32_16x16x32_bf16 v[26:29], v[180:183], v[70:73], 0
	ds_read_b128 v[180:183], v140 offset:65280
	s_waitcnt lgkmcnt(11)
	v_mfma_f32_16x16x32_bf16 v[26:29], v[184:187], v[66:69], v[26:29]
	ds_read_b128 v[184:187], v140 offset:65344
	s_waitcnt lgkmcnt(11)
	v_mfma_f32_16x16x32_bf16 v[26:29], v[188:191], v[34:37], v[26:29]
	ds_read_b128 v[188:191], v140 offset:65408
	s_waitcnt lgkmcnt(11)
	v_mfma_f32_16x16x32_bf16 v[26:29], v[192:195], v[74:77], v[26:29]
	ds_read_b128 v[192:195], v140 offset:65472
	s_waitcnt lgkmcnt(11)
	v_mfma_f32_16x16x32_bf16 v[38:41], v[196:199], v[70:73], 0
	s_waitcnt lgkmcnt(10)
	v_mfma_f32_16x16x32_bf16 v[38:41], v[220:223], v[66:69], v[38:41]
	s_waitcnt lgkmcnt(9)
	v_mfma_f32_16x16x32_bf16 v[38:41], v[224:227], v[34:37], v[38:41]
	s_waitcnt lgkmcnt(8)
	v_mfma_f32_16x16x32_bf16 v[38:41], v[228:231], v[74:77], v[38:41]
	s_waitcnt lgkmcnt(7)
	v_mfma_f32_16x16x32_bf16 v[30:33], v[232:235], v[70:73], 0
	s_waitcnt lgkmcnt(6)
	v_mfma_f32_16x16x32_bf16 v[30:33], v[236:239], v[66:69], v[30:33]
	s_waitcnt lgkmcnt(5)
	v_mfma_f32_16x16x32_bf16 v[30:33], v[240:243], v[34:37], v[30:33]
	s_waitcnt lgkmcnt(4)
	v_mfma_f32_16x16x32_bf16 v[30:33], v[244:247], v[74:77], v[30:33]
	s_waitcnt lgkmcnt(3)
	v_mfma_f32_16x16x32_bf16 v[70:73], v[180:183], v[70:73], 0
	s_waitcnt lgkmcnt(2)
	v_mfma_f32_16x16x32_bf16 v[66:69], v[184:187], v[66:69], v[70:73]
	s_waitcnt lgkmcnt(1)
	v_mfma_f32_16x16x32_bf16 v[34:37], v[188:191], v[34:37], v[66:69]
	s_waitcnt lgkmcnt(0)
	v_mfma_f32_16x16x32_bf16 v[34:37], v[192:195], v[74:77], v[34:37]
	v_max_f32_e32 v0, v5, v5
	v_max_f32_e32 v66, v4, v4
	v_max_f32_e32 v0, v66, v0
	v_max_f32_e32 v66, v65, v65
	v_max_f32_e32 v67, v64, v64
	v_max_f32_e32 v66, v67, v66
	v_max3_f32 v0, v2, v3, v0
	v_max3_f32 v66, v62, v63, v66
	v_max3_f32 v0, v0, s1, v66
	v_max_f32_e32 v66, v9, v9
	v_max_f32_e32 v67, v8, v8
	v_max_f32_e32 v66, v67, v66
	v_max_f32_e32 v67, v61, v61
	v_max_f32_e32 v68, v60, v60
	v_max_f32_e32 v67, v68, v67
	v_max3_f32 v66, v6, v7, v66
	v_max3_f32 v67, v58, v59, v67
	v_max3_f32 v0, v0, v66, v67
	v_max_f32_e32 v66, v13, v13
	v_max_f32_e32 v67, v12, v12
	v_max_f32_e32 v66, v67, v66
	v_max_f32_e32 v67, v57, v57
	v_max_f32_e32 v68, v56, v56
	v_max_f32_e32 v67, v68, v67
	v_max3_f32 v66, v10, v11, v66
	v_max3_f32 v67, v54, v55, v67
	v_max3_f32 v0, v0, v66, v67
	v_max_f32_e32 v66, v17, v17
	v_max_f32_e32 v67, v16, v16
	v_max_f32_e32 v66, v67, v66
	v_max_f32_e32 v67, v53, v53
	v_max_f32_e32 v68, v52, v52
	v_max_f32_e32 v67, v68, v67
	v_max3_f32 v66, v14, v15, v66
	v_max3_f32 v67, v50, v51, v67
	v_max3_f32 v0, v0, v66, v67
	v_max_f32_e32 v66, v21, v21
	v_max_f32_e32 v67, v20, v20
	v_max_f32_e32 v66, v67, v66
	v_max_f32_e32 v67, v49, v49
	v_max_f32_e32 v68, v48, v48
	v_max_f32_e32 v67, v68, v67
	v_max3_f32 v66, v18, v19, v66
	v_max3_f32 v67, v46, v47, v67
	v_max3_f32 v0, v0, v66, v67
	v_max_f32_e32 v66, v25, v25
	v_max_f32_e32 v67, v24, v24
	v_max_f32_e32 v66, v67, v66
	v_max_f32_e32 v67, v45, v45
	v_max_f32_e32 v68, v44, v44
	v_max_f32_e32 v67, v68, v67
	v_max3_f32 v66, v22, v23, v66
	v_max3_f32 v67, v42, v43, v67
	v_max3_f32 v0, v0, v66, v67
	v_max_f32_e32 v66, v29, v29
	v_max_f32_e32 v67, v28, v28
	v_max_f32_e32 v66, v67, v66
	v_max_f32_e32 v67, v41, v41
	v_max_f32_e32 v68, v40, v40
	v_max_f32_e32 v67, v68, v67
	v_max3_f32 v66, v26, v27, v66
	v_max3_f32 v67, v38, v39, v67
	v_max3_f32 v0, v0, v66, v67
	v_max_f32_e32 v66, v33, v33
	v_max_f32_e32 v67, v32, v32
	v_max_f32_e32 v66, v67, v66
	v_max_f32_e32 v67, v37, v37
	v_max_f32_e32 v68, v36, v36
	v_max_f32_e32 v67, v68, v67
	v_max3_f32 v66, v30, v31, v66
	v_max3_f32 v67, v34, v35, v67
	v_max3_f32 v66, v0, v66, v67
	v_and_b32_e32 v67, 64, v206
	v_xor_b32_e32 v0, 16, v206
	v_add_u32_e32 v67, 64, v67
	v_cmp_lt_i32_e32 vcc, v0, v67
	s_mov_b32 s1, 0xc2fc0000
	s_nop 0
	v_cndmask_b32_e32 v0, v206, v0, vcc
	v_lshlrev_b32_e32 v0, 2, v0
	ds_bpermute_b32 v68, v0, v66
	s_waitcnt lgkmcnt(0)
	v_max_f32_e32 v68, v68, v68
	v_max_f32_e32 v68, v66, v68
	v_xor_b32_e32 v66, 32, v206
	v_cmp_lt_i32_e32 vcc, v66, v67
	s_nop 1
	v_cndmask_b32_e32 v66, v206, v66, vcc
	v_lshlrev_b32_e32 v66, 2, v66
	ds_bpermute_b32 v67, v66, v68
	s_waitcnt lgkmcnt(0)
	v_max_f32_e32 v67, v67, v67
	v_max_f32_e32 v67, v68, v67
	v_sub_f32_e32 v2, v2, v67
	v_mul_f32_e32 v68, 0x3e0293ee, v2
	v_cmp_gt_f32_e32 vcc, s1, v68
	v_sub_f32_e32 v62, v62, v67
	v_sub_f32_e32 v3, v3, v67
	v_cndmask_b32_e32 v68, 0, v207, vcc
	v_fmac_f32_e32 v68, 0x3e0293ee, v2
	v_exp_f32_e32 v2, v68
	v_cndmask_b32_e32 v68, 0, v208, vcc
	v_sub_f32_e32 v63, v63, v67
	v_sub_f32_e32 v4, v4, v67
	v_ldexp_f32 v2, v2, v68
	v_mul_f32_e32 v68, 0x3e0293ee, v62
	v_cmp_gt_f32_e32 vcc, s1, v68
	v_sub_f32_e32 v64, v64, v67
	v_sub_f32_e32 v5, v5, v67
	v_cndmask_b32_e32 v68, 0, v207, vcc
	v_fmac_f32_e32 v68, 0x3e0293ee, v62
	v_exp_f32_e32 v62, v68
	v_cndmask_b32_e32 v68, 0, v208, vcc
	v_sub_f32_e32 v65, v65, v67
	v_sub_f32_e32 v6, v6, v67
	v_ldexp_f32 v62, v62, v68
	v_mul_f32_e32 v68, 0x3e0293ee, v3
	v_cmp_gt_f32_e32 vcc, s1, v68
	v_sub_f32_e32 v58, v58, v67
	v_sub_f32_e32 v7, v7, v67
	v_cndmask_b32_e32 v68, 0, v207, vcc
	v_fmac_f32_e32 v68, 0x3e0293ee, v3
	v_exp_f32_e32 v3, v68
	v_cndmask_b32_e32 v68, 0, v208, vcc
	v_sub_f32_e32 v59, v59, v67
	v_sub_f32_e32 v8, v8, v67
	v_ldexp_f32 v3, v3, v68
	v_mul_f32_e32 v68, 0x3e0293ee, v63
	v_cmp_gt_f32_e32 vcc, s1, v68
	v_bfe_u32 v72, v3, 16, 1
	v_add3_u32 v72, v3, v72, s60
	v_cndmask_b32_e32 v68, 0, v207, vcc
	v_fmac_f32_e32 v68, 0x3e0293ee, v63
	v_exp_f32_e32 v63, v68
	v_cndmask_b32_e32 v68, 0, v208, vcc
	v_sub_f32_e32 v60, v60, v67
	v_sub_f32_e32 v9, v9, v67
	v_ldexp_f32 v63, v63, v68
	v_mul_f32_e32 v68, 0x3e0293ee, v4
	v_cmp_gt_f32_e32 vcc, s1, v68
	v_sub_f32_e32 v61, v61, v67
	v_sub_f32_e32 v10, v10, v67
	v_cndmask_b32_e32 v68, 0, v207, vcc
	v_fmac_f32_e32 v68, 0x3e0293ee, v4
	v_exp_f32_e32 v4, v68
	v_cndmask_b32_e32 v68, 0, v208, vcc
	v_sub_f32_e32 v54, v54, v67
	v_sub_f32_e32 v11, v11, v67
	v_ldexp_f32 v4, v4, v68
	v_mul_f32_e32 v68, 0x3e0293ee, v64
	v_cmp_gt_f32_e32 vcc, s1, v68
	v_sub_f32_e32 v55, v55, v67
	v_sub_f32_e32 v12, v12, v67
	v_cndmask_b32_e32 v68, 0, v207, vcc
	v_fmac_f32_e32 v68, 0x3e0293ee, v64
	v_exp_f32_e32 v64, v68
	v_cndmask_b32_e32 v68, 0, v208, vcc
	v_sub_f32_e32 v56, v56, v67
	v_sub_f32_e32 v13, v13, v67
	v_ldexp_f32 v64, v64, v68
	v_mul_f32_e32 v68, 0x3e0293ee, v5
	v_cmp_gt_f32_e32 vcc, s1, v68
	v_sub_f32_e32 v57, v57, v67
	v_sub_f32_e32 v14, v14, v67
	v_cndmask_b32_e32 v68, 0, v207, vcc
	v_fmac_f32_e32 v68, 0x3e0293ee, v5
	v_exp_f32_e32 v5, v68
	v_cndmask_b32_e32 v68, 0, v208, vcc
	v_sub_f32_e32 v50, v50, v67
	v_sub_f32_e32 v15, v15, v67
	v_ldexp_f32 v5, v5, v68
	v_mul_f32_e32 v68, 0x3e0293ee, v65
	v_cmp_gt_f32_e32 vcc, s1, v68
	v_add_f32_e32 v69, v4, v5
	v_bfe_u32 v71, v5, 16, 1
	v_cndmask_b32_e32 v68, 0, v207, vcc
	v_fmac_f32_e32 v68, 0x3e0293ee, v65
	v_exp_f32_e32 v65, v68
	v_cndmask_b32_e32 v68, 0, v208, vcc
	v_sub_f32_e32 v51, v51, v67
	v_sub_f32_e32 v16, v16, v67
	v_ldexp_f32 v65, v65, v68
	v_add_f32_e32 v68, v2, v3
	v_add_f32_e32 v68, v68, v69
	v_add_f32_e32 v69, v62, v63
	v_add_f32_e32 v70, v64, v65
	v_add_f32_e32 v69, v69, v70
	v_add_f32_e32 v68, v68, v69
	v_bfe_u32 v69, v65, 16, 1
	v_bfe_u32 v70, v63, 16, 1
	v_add3_u32 v3, v5, v71, s60
	v_add3_u32 v63, v63, v70, s60
	v_add3_u32 v5, v65, v69, s60
	v_bfe_u32 v69, v4, 16, 1
	v_bfe_u32 v70, v62, 16, 1
	v_bfe_u32 v71, v64, 16, 1
	v_bfe_u32 v65, v2, 16, 1
	v_add3_u32 v64, v64, v71, s60
	v_add3_u32 v62, v62, v70, s60
	v_add3_u32 v4, v4, v69, s60
	v_add3_u32 v2, v2, v65, s60
	v_lshrrev_b32_e32 v65, 16, v4
	v_lshrrev_b32_e32 v4, 16, v62
	v_lshrrev_b32_e32 v62, 16, v64
	v_and_or_b32 v5, v5, s33, v62
	v_mul_f32_e32 v62, 0x3e0293ee, v6
	v_cmp_gt_f32_e32 vcc, s1, v62
	v_and_or_b32 v4, v63, s33, v4
	v_and_or_b32 v3, v3, s33, v65
	v_cndmask_b32_e32 v62, 0, v207, vcc
	v_fmac_f32_e32 v62, 0x3e0293ee, v6
	v_exp_f32_e32 v6, v62
	v_cndmask_b32_e32 v62, 0, v208, vcc
	v_sub_f32_e32 v52, v52, v67
	v_sub_f32_e32 v17, v17, v67
	v_ldexp_f32 v6, v6, v62
	v_mul_f32_e32 v62, 0x3e0293ee, v58
	v_cmp_gt_f32_e32 vcc, s1, v62
	v_sub_f32_e32 v53, v53, v67
	v_sub_f32_e32 v18, v18, v67
	v_cndmask_b32_e32 v62, 0, v207, vcc
	v_fmac_f32_e32 v62, 0x3e0293ee, v58
	v_exp_f32_e32 v58, v62
	v_cndmask_b32_e32 v62, 0, v208, vcc
	v_sub_f32_e32 v46, v46, v67
	v_sub_f32_e32 v19, v19, v67
	v_ldexp_f32 v58, v58, v62
	v_mul_f32_e32 v62, 0x3e0293ee, v7
	v_cmp_gt_f32_e32 vcc, s1, v62
	v_sub_f32_e32 v47, v47, v67
	v_sub_f32_e32 v20, v20, v67
	v_cndmask_b32_e32 v62, 0, v207, vcc
	v_fmac_f32_e32 v62, 0x3e0293ee, v7
	v_exp_f32_e32 v7, v62
	v_cndmask_b32_e32 v62, 0, v208, vcc
	v_sub_f32_e32 v48, v48, v67
	v_sub_f32_e32 v21, v21, v67
	v_ldexp_f32 v7, v7, v62
	v_mul_f32_e32 v62, 0x3e0293ee, v59
	v_cmp_gt_f32_e32 vcc, s1, v62
	v_sub_f32_e32 v49, v49, v67
	v_sub_f32_e32 v22, v22, v67
	v_cndmask_b32_e32 v62, 0, v207, vcc
	v_fmac_f32_e32 v62, 0x3e0293ee, v59
	v_exp_f32_e32 v59, v62
	v_cndmask_b32_e32 v62, 0, v208, vcc
	v_sub_f32_e32 v42, v42, v67
	v_sub_f32_e32 v23, v23, v67
	v_ldexp_f32 v59, v59, v62
	v_mul_f32_e32 v62, 0x3e0293ee, v8
	v_cmp_gt_f32_e32 vcc, s1, v62
	v_sub_f32_e32 v43, v43, v67
	v_sub_f32_e32 v24, v24, v67
	v_cndmask_b32_e32 v62, 0, v207, vcc
	v_fmac_f32_e32 v62, 0x3e0293ee, v8
	v_exp_f32_e32 v8, v62
	v_cndmask_b32_e32 v62, 0, v208, vcc
	v_sub_f32_e32 v44, v44, v67
	v_sub_f32_e32 v25, v25, v67
	v_ldexp_f32 v8, v8, v62
	v_mul_f32_e32 v62, 0x3e0293ee, v60
	v_cmp_gt_f32_e32 vcc, s1, v62
	v_sub_f32_e32 v45, v45, v67
	v_sub_f32_e32 v26, v26, v67
	v_cndmask_b32_e32 v62, 0, v207, vcc
	v_fmac_f32_e32 v62, 0x3e0293ee, v60
	v_exp_f32_e32 v60, v62
	v_cndmask_b32_e32 v62, 0, v208, vcc
	v_sub_f32_e32 v38, v38, v67
	v_sub_f32_e32 v27, v27, v67
	v_ldexp_f32 v60, v60, v62
	v_mul_f32_e32 v62, 0x3e0293ee, v9
	v_cmp_gt_f32_e32 vcc, s1, v62
	v_sub_f32_e32 v39, v39, v67
	v_sub_f32_e32 v28, v28, v67
	v_cndmask_b32_e32 v62, 0, v207, vcc
	v_fmac_f32_e32 v62, 0x3e0293ee, v9
	v_exp_f32_e32 v9, v62
	v_cndmask_b32_e32 v62, 0, v208, vcc
	v_sub_f32_e32 v40, v40, v67
	v_sub_f32_e32 v29, v29, v67
	v_ldexp_f32 v9, v9, v62
	v_mul_f32_e32 v62, 0x3e0293ee, v61
	v_cmp_gt_f32_e32 vcc, s1, v62
	v_add_f32_e32 v63, v8, v9
	v_bfe_u32 v65, v9, 16, 1
	v_cndmask_b32_e32 v62, 0, v207, vcc
	v_fmac_f32_e32 v62, 0x3e0293ee, v61
	v_exp_f32_e32 v61, v62
	v_cndmask_b32_e32 v62, 0, v208, vcc
	v_sub_f32_e32 v41, v41, v67
	v_sub_f32_e32 v30, v30, v67
	v_ldexp_f32 v61, v61, v62
	v_add_f32_e32 v62, v6, v7
	v_add_f32_e32 v62, v62, v63
	v_add_f32_e32 v63, v58, v59
	v_add_f32_e32 v64, v60, v61
	v_add_f32_e32 v63, v63, v64
	v_add_f32_e32 v62, v62, v63
	v_add_f32_e32 v62, v68, v62
	v_bfe_u32 v63, v61, 16, 1
	v_bfe_u32 v64, v59, 16, 1
	v_bfe_u32 v68, v7, 16, 1
	v_add3_u32 v68, v7, v68, s60
	v_add3_u32 v7, v9, v65, s60
	v_add3_u32 v59, v59, v64, s60
	v_add3_u32 v9, v61, v63, s60
	v_bfe_u32 v63, v8, 16, 1
	v_bfe_u32 v64, v58, 16, 1
	v_bfe_u32 v65, v60, 16, 1
	v_bfe_u32 v61, v6, 16, 1
	v_add3_u32 v60, v60, v65, s60
	v_add3_u32 v58, v58, v64, s60
	v_add3_u32 v8, v8, v63, s60
	v_add3_u32 v6, v6, v61, s60
	v_lshrrev_b32_e32 v61, 16, v8
	v_lshrrev_b32_e32 v8, 16, v58
	v_lshrrev_b32_e32 v58, 16, v60
	v_and_or_b32 v9, v9, s33, v58
	v_mul_f32_e32 v58, 0x3e0293ee, v10
	v_cmp_gt_f32_e32 vcc, s1, v58
	v_and_or_b32 v8, v59, s33, v8
	v_and_or_b32 v7, v7, s33, v61
	v_cndmask_b32_e32 v58, 0, v207, vcc
	v_fmac_f32_e32 v58, 0x3e0293ee, v10
	v_exp_f32_e32 v10, v58
	v_cndmask_b32_e32 v58, 0, v208, vcc
	v_sub_f32_e32 v34, v34, v67
	v_sub_f32_e32 v31, v31, v67
	v_ldexp_f32 v10, v10, v58
	v_mul_f32_e32 v58, 0x3e0293ee, v54
	v_cmp_gt_f32_e32 vcc, s1, v58
	v_sub_f32_e32 v35, v35, v67
	v_sub_f32_e32 v32, v32, v67
	v_cndmask_b32_e32 v58, 0, v207, vcc
	v_fmac_f32_e32 v58, 0x3e0293ee, v54
	v_exp_f32_e32 v54, v58
	v_cndmask_b32_e32 v58, 0, v208, vcc
	v_sub_f32_e32 v36, v36, v67
	v_sub_f32_e32 v33, v33, v67
	v_ldexp_f32 v54, v54, v58
	v_mul_f32_e32 v58, 0x3e0293ee, v11
	v_cmp_gt_f32_e32 vcc, s1, v58
	v_sub_f32_e32 v37, v37, v67
	v_lshrrev_b32_e32 v2, 16, v2
	v_cndmask_b32_e32 v58, 0, v207, vcc
	v_fmac_f32_e32 v58, 0x3e0293ee, v11
	v_exp_f32_e32 v11, v58
	v_cndmask_b32_e32 v58, 0, v208, vcc
	v_and_or_b32 v2, v72, s33, v2
	v_lshrrev_b32_e32 v6, 16, v6
	v_ldexp_f32 v11, v11, v58
	v_mul_f32_e32 v58, 0x3e0293ee, v55
	v_cmp_gt_f32_e32 vcc, s1, v58
	v_and_or_b32 v6, v68, s33, v6
	s_nop 0
	v_cndmask_b32_e32 v58, 0, v207, vcc
	v_fmac_f32_e32 v58, 0x3e0293ee, v55
	v_exp_f32_e32 v55, v58
	v_cndmask_b32_e32 v58, 0, v208, vcc
	v_ldexp_f32 v55, v55, v58
	v_mul_f32_e32 v58, 0x3e0293ee, v12
	v_cmp_gt_f32_e32 vcc, s1, v58
	s_nop 1
	v_cndmask_b32_e32 v58, 0, v207, vcc
	v_fmac_f32_e32 v58, 0x3e0293ee, v12
	v_exp_f32_e32 v12, v58
	v_cndmask_b32_e32 v58, 0, v208, vcc
	v_ldexp_f32 v12, v12, v58
	v_mul_f32_e32 v58, 0x3e0293ee, v56
	v_cmp_gt_f32_e32 vcc, s1, v58
	s_nop 1
	v_cndmask_b32_e32 v58, 0, v207, vcc
	v_fmac_f32_e32 v58, 0x3e0293ee, v56
	v_exp_f32_e32 v56, v58
	v_cndmask_b32_e32 v58, 0, v208, vcc
	v_ldexp_f32 v56, v56, v58
	v_mul_f32_e32 v58, 0x3e0293ee, v13
	v_cmp_gt_f32_e32 vcc, s1, v58
	s_nop 1
	v_cndmask_b32_e32 v58, 0, v207, vcc
	v_fmac_f32_e32 v58, 0x3e0293ee, v13
	v_exp_f32_e32 v13, v58
	v_cndmask_b32_e32 v58, 0, v208, vcc
	v_ldexp_f32 v13, v13, v58
	v_mul_f32_e32 v58, 0x3e0293ee, v57
	v_cmp_gt_f32_e32 vcc, s1, v58
	v_add_f32_e32 v59, v12, v13
	v_bfe_u32 v61, v13, 16, 1
	v_cndmask_b32_e32 v58, 0, v207, vcc
	v_fmac_f32_e32 v58, 0x3e0293ee, v57
	v_exp_f32_e32 v57, v58
	v_cndmask_b32_e32 v58, 0, v208, vcc
	v_ldexp_f32 v57, v57, v58
	v_add_f32_e32 v58, v10, v11
	v_add_f32_e32 v58, v58, v59
	v_add_f32_e32 v59, v54, v55
	v_add_f32_e32 v60, v56, v57
	v_add_f32_e32 v59, v59, v60
	v_add_f32_e32 v58, v58, v59
	v_add_f32_e32 v58, v58, v62
	v_bfe_u32 v59, v57, 16, 1
	v_bfe_u32 v60, v55, 16, 1
	v_bfe_u32 v62, v11, 16, 1
	v_add3_u32 v62, v11, v62, s60
	v_add3_u32 v11, v13, v61, s60
	v_add3_u32 v55, v55, v60, s60
	v_add3_u32 v13, v57, v59, s60
	v_bfe_u32 v59, v12, 16, 1
	v_bfe_u32 v60, v54, 16, 1
	v_bfe_u32 v61, v56, 16, 1
	v_bfe_u32 v57, v10, 16, 1
	v_add3_u32 v56, v56, v61, s60
	v_add3_u32 v54, v54, v60, s60
	v_add3_u32 v12, v12, v59, s60
	v_add3_u32 v10, v10, v57, s60
	v_lshrrev_b32_e32 v57, 16, v12
	v_lshrrev_b32_e32 v12, 16, v54
	v_lshrrev_b32_e32 v54, 16, v56
	v_and_or_b32 v13, v13, s33, v54
	v_mul_f32_e32 v54, 0x3e0293ee, v14
	v_cmp_gt_f32_e32 vcc, s1, v54
	v_and_or_b32 v12, v55, s33, v12
	v_and_or_b32 v11, v11, s33, v57
	v_cndmask_b32_e32 v54, 0, v207, vcc
	v_fmac_f32_e32 v54, 0x3e0293ee, v14
	v_exp_f32_e32 v14, v54
	v_cndmask_b32_e32 v54, 0, v208, vcc
	v_lshrrev_b32_e32 v10, 16, v10
	v_and_or_b32 v10, v62, s33, v10
	v_ldexp_f32 v14, v14, v54
	v_mul_f32_e32 v54, 0x3e0293ee, v50
	v_cmp_gt_f32_e32 vcc, s1, v54
	s_nop 1
	v_cndmask_b32_e32 v54, 0, v207, vcc
	v_fmac_f32_e32 v54, 0x3e0293ee, v50
	v_exp_f32_e32 v50, v54
	v_cndmask_b32_e32 v54, 0, v208, vcc
	v_ldexp_f32 v50, v50, v54
	v_mul_f32_e32 v54, 0x3e0293ee, v15
	v_cmp_gt_f32_e32 vcc, s1, v54
	s_nop 1
	v_cndmask_b32_e32 v54, 0, v207, vcc
	v_fmac_f32_e32 v54, 0x3e0293ee, v15
	v_exp_f32_e32 v15, v54
	v_cndmask_b32_e32 v54, 0, v208, vcc
	v_ldexp_f32 v15, v15, v54
	v_mul_f32_e32 v54, 0x3e0293ee, v51
	v_cmp_gt_f32_e32 vcc, s1, v54
	s_nop 1
	v_cndmask_b32_e32 v54, 0, v207, vcc
	v_fmac_f32_e32 v54, 0x3e0293ee, v51
	v_exp_f32_e32 v51, v54
	v_cndmask_b32_e32 v54, 0, v208, vcc
	v_ldexp_f32 v51, v51, v54
	v_mul_f32_e32 v54, 0x3e0293ee, v16
	v_cmp_gt_f32_e32 vcc, s1, v54
	s_nop 1
	v_cndmask_b32_e32 v54, 0, v207, vcc
	v_fmac_f32_e32 v54, 0x3e0293ee, v16
	v_exp_f32_e32 v16, v54
	v_cndmask_b32_e32 v54, 0, v208, vcc
	v_ldexp_f32 v16, v16, v54
	v_mul_f32_e32 v54, 0x3e0293ee, v52
	v_cmp_gt_f32_e32 vcc, s1, v54
	s_nop 1
	v_cndmask_b32_e32 v54, 0, v207, vcc
	v_fmac_f32_e32 v54, 0x3e0293ee, v52
	v_exp_f32_e32 v52, v54
	v_cndmask_b32_e32 v54, 0, v208, vcc
	v_ldexp_f32 v52, v52, v54
	v_mul_f32_e32 v54, 0x3e0293ee, v17
	v_cmp_gt_f32_e32 vcc, s1, v54
	s_nop 1
	v_cndmask_b32_e32 v54, 0, v207, vcc
	v_fmac_f32_e32 v54, 0x3e0293ee, v17
	v_exp_f32_e32 v17, v54
	v_cndmask_b32_e32 v54, 0, v208, vcc
	v_ldexp_f32 v17, v17, v54
	v_mul_f32_e32 v54, 0x3e0293ee, v53
	v_cmp_gt_f32_e32 vcc, s1, v54
	v_add_f32_e32 v55, v16, v17
	v_bfe_u32 v57, v17, 16, 1
	v_cndmask_b32_e32 v54, 0, v207, vcc
	v_fmac_f32_e32 v54, 0x3e0293ee, v53
	v_exp_f32_e32 v53, v54
	v_cndmask_b32_e32 v54, 0, v208, vcc
	v_ldexp_f32 v53, v53, v54
	v_add_f32_e32 v54, v14, v15
	v_add_f32_e32 v54, v54, v55
	v_add_f32_e32 v55, v50, v51
	v_add_f32_e32 v56, v52, v53
	v_add_f32_e32 v55, v55, v56
	v_add_f32_e32 v54, v54, v55
	v_add_f32_e32 v54, v54, v58
	v_bfe_u32 v55, v53, 16, 1
	v_bfe_u32 v56, v51, 16, 1
	v_bfe_u32 v58, v15, 16, 1
	v_add3_u32 v58, v15, v58, s60
	v_add3_u32 v15, v17, v57, s60
	v_add3_u32 v51, v51, v56, s60
	v_add3_u32 v17, v53, v55, s60
	v_bfe_u32 v55, v16, 16, 1
	v_bfe_u32 v56, v50, 16, 1
	v_bfe_u32 v57, v52, 16, 1
	v_bfe_u32 v53, v14, 16, 1
	v_add3_u32 v52, v52, v57, s60
	v_add3_u32 v50, v50, v56, s60
	v_add3_u32 v16, v16, v55, s60
	v_add3_u32 v14, v14, v53, s60
	v_lshrrev_b32_e32 v53, 16, v16
	v_lshrrev_b32_e32 v16, 16, v50
	v_lshrrev_b32_e32 v50, 16, v52
	v_and_or_b32 v17, v17, s33, v50
	v_mul_f32_e32 v50, 0x3e0293ee, v18
	v_cmp_gt_f32_e32 vcc, s1, v50
	v_and_or_b32 v16, v51, s33, v16
	v_and_or_b32 v15, v15, s33, v53
	v_cndmask_b32_e32 v50, 0, v207, vcc
	v_fmac_f32_e32 v50, 0x3e0293ee, v18
	v_exp_f32_e32 v18, v50
	v_cndmask_b32_e32 v50, 0, v208, vcc
	v_lshrrev_b32_e32 v14, 16, v14
	v_and_or_b32 v14, v58, s33, v14
	v_ldexp_f32 v18, v18, v50
	v_mul_f32_e32 v50, 0x3e0293ee, v46
	v_cmp_gt_f32_e32 vcc, s1, v50
	s_nop 1
	v_cndmask_b32_e32 v50, 0, v207, vcc
	v_fmac_f32_e32 v50, 0x3e0293ee, v46
	v_exp_f32_e32 v46, v50
	v_cndmask_b32_e32 v50, 0, v208, vcc
	v_ldexp_f32 v46, v46, v50
	v_mul_f32_e32 v50, 0x3e0293ee, v19
	v_cmp_gt_f32_e32 vcc, s1, v50
	s_nop 1
	v_cndmask_b32_e32 v50, 0, v207, vcc
	v_fmac_f32_e32 v50, 0x3e0293ee, v19
	v_exp_f32_e32 v19, v50
	v_cndmask_b32_e32 v50, 0, v208, vcc
	v_ldexp_f32 v19, v19, v50
	v_mul_f32_e32 v50, 0x3e0293ee, v47
	v_cmp_gt_f32_e32 vcc, s1, v50
	s_nop 1
	v_cndmask_b32_e32 v50, 0, v207, vcc
	v_fmac_f32_e32 v50, 0x3e0293ee, v47
	v_exp_f32_e32 v47, v50
	v_cndmask_b32_e32 v50, 0, v208, vcc
	v_ldexp_f32 v47, v47, v50
	v_mul_f32_e32 v50, 0x3e0293ee, v20
	v_cmp_gt_f32_e32 vcc, s1, v50
	s_nop 1
	v_cndmask_b32_e32 v50, 0, v207, vcc
	v_fmac_f32_e32 v50, 0x3e0293ee, v20
	v_exp_f32_e32 v20, v50
	v_cndmask_b32_e32 v50, 0, v208, vcc
	v_ldexp_f32 v20, v20, v50
	v_mul_f32_e32 v50, 0x3e0293ee, v48
	v_cmp_gt_f32_e32 vcc, s1, v50
	s_nop 1
	v_cndmask_b32_e32 v50, 0, v207, vcc
	v_fmac_f32_e32 v50, 0x3e0293ee, v48
	v_exp_f32_e32 v48, v50
	v_cndmask_b32_e32 v50, 0, v208, vcc
	v_ldexp_f32 v48, v48, v50
	v_mul_f32_e32 v50, 0x3e0293ee, v21
	v_cmp_gt_f32_e32 vcc, s1, v50
	s_nop 1
	v_cndmask_b32_e32 v50, 0, v207, vcc
	v_fmac_f32_e32 v50, 0x3e0293ee, v21
	v_exp_f32_e32 v21, v50
	v_cndmask_b32_e32 v50, 0, v208, vcc
	v_ldexp_f32 v21, v21, v50
	v_mul_f32_e32 v50, 0x3e0293ee, v49
	v_cmp_gt_f32_e32 vcc, s1, v50
	v_add_f32_e32 v51, v20, v21
	v_bfe_u32 v53, v21, 16, 1
	v_cndmask_b32_e32 v50, 0, v207, vcc
	v_fmac_f32_e32 v50, 0x3e0293ee, v49
	v_exp_f32_e32 v49, v50
	v_cndmask_b32_e32 v50, 0, v208, vcc
	v_ldexp_f32 v49, v49, v50
	v_add_f32_e32 v50, v18, v19
	v_add_f32_e32 v50, v50, v51
	v_add_f32_e32 v51, v46, v47
	v_add_f32_e32 v52, v48, v49
	v_add_f32_e32 v51, v51, v52
	v_add_f32_e32 v50, v50, v51
	v_add_f32_e32 v50, v50, v54
	v_bfe_u32 v51, v49, 16, 1
	v_bfe_u32 v52, v47, 16, 1
	v_bfe_u32 v54, v19, 16, 1
	v_add3_u32 v54, v19, v54, s60
	v_add3_u32 v19, v21, v53, s60
	v_add3_u32 v47, v47, v52, s60
	v_add3_u32 v21, v49, v51, s60
	v_bfe_u32 v51, v20, 16, 1
	v_bfe_u32 v52, v46, 16, 1
	v_bfe_u32 v53, v48, 16, 1
	v_bfe_u32 v49, v18, 16, 1
	v_add3_u32 v48, v48, v53, s60
	v_add3_u32 v46, v46, v52, s60
	v_add3_u32 v20, v20, v51, s60
	v_add3_u32 v18, v18, v49, s60
	v_lshrrev_b32_e32 v49, 16, v20
	v_lshrrev_b32_e32 v20, 16, v46
	v_lshrrev_b32_e32 v46, 16, v48
	v_and_or_b32 v21, v21, s33, v46
	v_mul_f32_e32 v46, 0x3e0293ee, v22
	v_cmp_gt_f32_e32 vcc, s1, v46
	v_and_or_b32 v20, v47, s33, v20
	v_and_or_b32 v19, v19, s33, v49
	v_cndmask_b32_e32 v46, 0, v207, vcc
	v_fmac_f32_e32 v46, 0x3e0293ee, v22
	v_exp_f32_e32 v22, v46
	v_cndmask_b32_e32 v46, 0, v208, vcc
	v_lshrrev_b32_e32 v18, 16, v18
	v_and_or_b32 v18, v54, s33, v18
	v_ldexp_f32 v22, v22, v46
	v_mul_f32_e32 v46, 0x3e0293ee, v42
	v_cmp_gt_f32_e32 vcc, s1, v46
	s_nop 1
	v_cndmask_b32_e32 v46, 0, v207, vcc
	v_fmac_f32_e32 v46, 0x3e0293ee, v42
	v_exp_f32_e32 v42, v46
	v_cndmask_b32_e32 v46, 0, v208, vcc
	v_ldexp_f32 v42, v42, v46
	v_mul_f32_e32 v46, 0x3e0293ee, v23
	v_cmp_gt_f32_e32 vcc, s1, v46
	s_nop 1
	v_cndmask_b32_e32 v46, 0, v207, vcc
	v_fmac_f32_e32 v46, 0x3e0293ee, v23
	v_exp_f32_e32 v23, v46
	v_cndmask_b32_e32 v46, 0, v208, vcc
	v_ldexp_f32 v23, v23, v46
	v_mul_f32_e32 v46, 0x3e0293ee, v43
	v_cmp_gt_f32_e32 vcc, s1, v46
	s_nop 1
	v_cndmask_b32_e32 v46, 0, v207, vcc
	v_fmac_f32_e32 v46, 0x3e0293ee, v43
	v_exp_f32_e32 v43, v46
	v_cndmask_b32_e32 v46, 0, v208, vcc
	v_ldexp_f32 v43, v43, v46
	v_mul_f32_e32 v46, 0x3e0293ee, v24
	v_cmp_gt_f32_e32 vcc, s1, v46
	s_nop 1
	v_cndmask_b32_e32 v46, 0, v207, vcc
	v_fmac_f32_e32 v46, 0x3e0293ee, v24
	v_exp_f32_e32 v24, v46
	v_cndmask_b32_e32 v46, 0, v208, vcc
	v_ldexp_f32 v24, v24, v46
	v_mul_f32_e32 v46, 0x3e0293ee, v44
	v_cmp_gt_f32_e32 vcc, s1, v46
	s_nop 1
	v_cndmask_b32_e32 v46, 0, v207, vcc
	v_fmac_f32_e32 v46, 0x3e0293ee, v44
	v_exp_f32_e32 v44, v46
	v_cndmask_b32_e32 v46, 0, v208, vcc
	v_ldexp_f32 v44, v44, v46
	v_mul_f32_e32 v46, 0x3e0293ee, v25
	v_cmp_gt_f32_e32 vcc, s1, v46
	s_nop 1
	v_cndmask_b32_e32 v46, 0, v207, vcc
	v_fmac_f32_e32 v46, 0x3e0293ee, v25
	v_exp_f32_e32 v25, v46
	v_cndmask_b32_e32 v46, 0, v208, vcc
	v_ldexp_f32 v25, v25, v46
	v_mul_f32_e32 v46, 0x3e0293ee, v45
	v_cmp_gt_f32_e32 vcc, s1, v46
	v_add_f32_e32 v47, v24, v25
	v_bfe_u32 v49, v25, 16, 1
	v_cndmask_b32_e32 v46, 0, v207, vcc
	v_fmac_f32_e32 v46, 0x3e0293ee, v45
	v_exp_f32_e32 v45, v46
	v_cndmask_b32_e32 v46, 0, v208, vcc
	v_ldexp_f32 v45, v45, v46
	v_add_f32_e32 v46, v22, v23
	v_add_f32_e32 v46, v46, v47
	v_add_f32_e32 v47, v42, v43
	v_add_f32_e32 v48, v44, v45
	v_add_f32_e32 v47, v47, v48
	v_add_f32_e32 v46, v46, v47
	v_add_f32_e32 v46, v46, v50
	v_bfe_u32 v47, v45, 16, 1
	v_bfe_u32 v48, v43, 16, 1
	v_bfe_u32 v50, v23, 16, 1
	v_add3_u32 v50, v23, v50, s60
	v_add3_u32 v23, v25, v49, s60
	v_add3_u32 v43, v43, v48, s60
	v_add3_u32 v25, v45, v47, s60
	v_bfe_u32 v47, v24, 16, 1
	v_bfe_u32 v48, v42, 16, 1
	v_bfe_u32 v49, v44, 16, 1
	v_bfe_u32 v45, v22, 16, 1
	v_add3_u32 v44, v44, v49, s60
	v_add3_u32 v42, v42, v48, s60
	v_add3_u32 v24, v24, v47, s60
	v_add3_u32 v22, v22, v45, s60
	v_lshrrev_b32_e32 v45, 16, v24
	v_lshrrev_b32_e32 v24, 16, v42
	v_lshrrev_b32_e32 v42, 16, v44
	v_and_or_b32 v25, v25, s33, v42
	v_mul_f32_e32 v42, 0x3e0293ee, v26
	v_cmp_gt_f32_e32 vcc, s1, v42
	v_and_or_b32 v24, v43, s33, v24
	v_and_or_b32 v23, v23, s33, v45
	v_cndmask_b32_e32 v42, 0, v207, vcc
	v_fmac_f32_e32 v42, 0x3e0293ee, v26
	v_exp_f32_e32 v26, v42
	v_cndmask_b32_e32 v42, 0, v208, vcc
	v_lshrrev_b32_e32 v22, 16, v22
	v_and_or_b32 v22, v50, s33, v22
	v_ldexp_f32 v26, v26, v42
	v_mul_f32_e32 v42, 0x3e0293ee, v38
	v_cmp_gt_f32_e32 vcc, s1, v42
	s_nop 1
	v_cndmask_b32_e32 v42, 0, v207, vcc
	v_fmac_f32_e32 v42, 0x3e0293ee, v38
	v_exp_f32_e32 v38, v42
	v_cndmask_b32_e32 v42, 0, v208, vcc
	v_ldexp_f32 v38, v38, v42
	v_mul_f32_e32 v42, 0x3e0293ee, v27
	v_cmp_gt_f32_e32 vcc, s1, v42
	s_nop 1
	v_cndmask_b32_e32 v42, 0, v207, vcc
	v_fmac_f32_e32 v42, 0x3e0293ee, v27
	v_exp_f32_e32 v27, v42
	v_cndmask_b32_e32 v42, 0, v208, vcc
	v_ldexp_f32 v27, v27, v42
	v_mul_f32_e32 v42, 0x3e0293ee, v39
	v_cmp_gt_f32_e32 vcc, s1, v42
	s_nop 1
	v_cndmask_b32_e32 v42, 0, v207, vcc
	v_fmac_f32_e32 v42, 0x3e0293ee, v39
	v_exp_f32_e32 v39, v42
	v_cndmask_b32_e32 v42, 0, v208, vcc
	v_ldexp_f32 v39, v39, v42
	v_mul_f32_e32 v42, 0x3e0293ee, v28
	v_cmp_gt_f32_e32 vcc, s1, v42
	s_nop 1
	v_cndmask_b32_e32 v42, 0, v207, vcc
	v_fmac_f32_e32 v42, 0x3e0293ee, v28
	v_exp_f32_e32 v28, v42
	v_cndmask_b32_e32 v42, 0, v208, vcc
	v_ldexp_f32 v28, v28, v42
	v_mul_f32_e32 v42, 0x3e0293ee, v40
	v_cmp_gt_f32_e32 vcc, s1, v42
	s_nop 1
	v_cndmask_b32_e32 v42, 0, v207, vcc
	v_fmac_f32_e32 v42, 0x3e0293ee, v40
	v_exp_f32_e32 v40, v42
	v_cndmask_b32_e32 v42, 0, v208, vcc
	v_ldexp_f32 v40, v40, v42
	v_mul_f32_e32 v42, 0x3e0293ee, v29
	v_cmp_gt_f32_e32 vcc, s1, v42
	s_nop 1
	v_cndmask_b32_e32 v42, 0, v207, vcc
	v_fmac_f32_e32 v42, 0x3e0293ee, v29
	v_exp_f32_e32 v29, v42
	v_cndmask_b32_e32 v42, 0, v208, vcc
	v_ldexp_f32 v29, v29, v42
	v_mul_f32_e32 v42, 0x3e0293ee, v41
	v_cmp_gt_f32_e32 vcc, s1, v42
	v_add_f32_e32 v43, v28, v29
	v_bfe_u32 v45, v29, 16, 1
	v_cndmask_b32_e32 v42, 0, v207, vcc
	v_fmac_f32_e32 v42, 0x3e0293ee, v41
	v_exp_f32_e32 v41, v42
	v_cndmask_b32_e32 v42, 0, v208, vcc
	v_ldexp_f32 v41, v41, v42
	v_add_f32_e32 v42, v26, v27
	v_add_f32_e32 v42, v42, v43
	v_add_f32_e32 v43, v38, v39
	v_add_f32_e32 v44, v40, v41
	v_add_f32_e32 v43, v43, v44
	v_add_f32_e32 v42, v42, v43
	v_add_f32_e32 v42, v42, v46
	v_bfe_u32 v43, v41, 16, 1
	v_bfe_u32 v44, v39, 16, 1
	v_bfe_u32 v46, v27, 16, 1
	v_add3_u32 v46, v27, v46, s60
	v_add3_u32 v27, v29, v45, s60
	v_add3_u32 v39, v39, v44, s60
	v_add3_u32 v29, v41, v43, s60
	v_bfe_u32 v43, v28, 16, 1
	v_bfe_u32 v44, v38, 16, 1
	v_bfe_u32 v45, v40, 16, 1
	v_bfe_u32 v41, v26, 16, 1
	v_add3_u32 v40, v40, v45, s60
	v_add3_u32 v38, v38, v44, s60
	v_add3_u32 v28, v28, v43, s60
	v_add3_u32 v26, v26, v41, s60
	v_lshrrev_b32_e32 v41, 16, v28
	v_lshrrev_b32_e32 v28, 16, v38
	v_lshrrev_b32_e32 v38, 16, v40
	v_and_or_b32 v29, v29, s33, v38
	v_mul_f32_e32 v38, 0x3e0293ee, v30
	v_cmp_gt_f32_e32 vcc, s1, v38
	v_and_or_b32 v28, v39, s33, v28
	v_and_or_b32 v27, v27, s33, v41
	v_cndmask_b32_e32 v38, 0, v207, vcc
	v_fmac_f32_e32 v38, 0x3e0293ee, v30
	v_exp_f32_e32 v30, v38
	v_cndmask_b32_e32 v38, 0, v208, vcc
	v_lshrrev_b32_e32 v26, 16, v26
	v_and_or_b32 v26, v46, s33, v26
	v_ldexp_f32 v30, v30, v38
	v_mul_f32_e32 v38, 0x3e0293ee, v34
	v_cmp_gt_f32_e32 vcc, s1, v38
	s_nop 1
	v_cndmask_b32_e32 v38, 0, v207, vcc
	v_fmac_f32_e32 v38, 0x3e0293ee, v34
	v_exp_f32_e32 v34, v38
	v_cndmask_b32_e32 v38, 0, v208, vcc
	v_ldexp_f32 v34, v34, v38
	v_mul_f32_e32 v38, 0x3e0293ee, v31
	v_cmp_gt_f32_e32 vcc, s1, v38
	s_nop 1
	v_cndmask_b32_e32 v38, 0, v207, vcc
	v_fmac_f32_e32 v38, 0x3e0293ee, v31
	v_exp_f32_e32 v31, v38
	v_cndmask_b32_e32 v38, 0, v208, vcc
	v_ldexp_f32 v31, v31, v38
	v_mul_f32_e32 v38, 0x3e0293ee, v35
	v_cmp_gt_f32_e32 vcc, s1, v38
	s_nop 1
	v_cndmask_b32_e32 v38, 0, v207, vcc
	v_fmac_f32_e32 v38, 0x3e0293ee, v35
	v_exp_f32_e32 v35, v38
	v_cndmask_b32_e32 v38, 0, v208, vcc
	v_ldexp_f32 v35, v35, v38
	v_mul_f32_e32 v38, 0x3e0293ee, v32
	v_cmp_gt_f32_e32 vcc, s1, v38
	s_nop 1
	v_cndmask_b32_e32 v38, 0, v207, vcc
	v_fmac_f32_e32 v38, 0x3e0293ee, v32
	v_exp_f32_e32 v32, v38
	v_cndmask_b32_e32 v38, 0, v208, vcc
	v_ldexp_f32 v32, v32, v38
	v_mul_f32_e32 v38, 0x3e0293ee, v36
	v_cmp_gt_f32_e32 vcc, s1, v38
	s_nop 1
	v_cndmask_b32_e32 v38, 0, v207, vcc
	v_fmac_f32_e32 v38, 0x3e0293ee, v36
	v_exp_f32_e32 v36, v38
	v_cndmask_b32_e32 v38, 0, v208, vcc
	v_ldexp_f32 v36, v36, v38
	v_mul_f32_e32 v38, 0x3e0293ee, v33
	v_cmp_gt_f32_e32 vcc, s1, v38
	s_nop 1
	v_cndmask_b32_e32 v38, 0, v207, vcc
	v_fmac_f32_e32 v38, 0x3e0293ee, v33
	v_exp_f32_e32 v33, v38
	v_cndmask_b32_e32 v38, 0, v208, vcc
	v_ldexp_f32 v33, v33, v38
	v_mul_f32_e32 v38, 0x3e0293ee, v37
	v_cmp_gt_f32_e32 vcc, s1, v38
	v_add_f32_e32 v39, v32, v33
	v_bfe_u32 v41, v33, 16, 1
	v_cndmask_b32_e32 v38, 0, v207, vcc
	v_fmac_f32_e32 v38, 0x3e0293ee, v37
	v_exp_f32_e32 v37, v38
	v_cndmask_b32_e32 v38, 0, v208, vcc
	v_ldexp_f32 v37, v37, v38
	v_add_f32_e32 v38, v30, v31
	v_add_f32_e32 v38, v38, v39
	v_add_f32_e32 v39, v34, v35
	v_add_f32_e32 v40, v36, v37
	v_add_f32_e32 v39, v39, v40
	v_add_f32_e32 v38, v38, v39
	v_add_f32_e32 v38, v38, v42
	ds_bpermute_b32 v0, v0, v38
	v_bfe_u32 v39, v37, 16, 1
	v_bfe_u32 v40, v35, 16, 1
	v_bfe_u32 v42, v31, 16, 1
	v_add3_u32 v42, v31, v42, s60
	v_add3_u32 v31, v33, v41, s60
	v_add3_u32 v35, v35, v40, s60
	v_add3_u32 v33, v37, v39, s60
	v_bfe_u32 v39, v32, 16, 1
	v_bfe_u32 v40, v34, 16, 1
	v_bfe_u32 v41, v36, 16, 1
	v_bfe_u32 v37, v30, 16, 1
	v_add3_u32 v36, v36, v41, s60
	v_add3_u32 v34, v34, v40, s60
	v_add3_u32 v32, v32, v39, s60
	v_add3_u32 v30, v30, v37, s60
	v_lshrrev_b32_e32 v37, 16, v32
	v_lshrrev_b32_e32 v32, 16, v34
	v_lshrrev_b32_e32 v34, 16, v36
	s_waitcnt lgkmcnt(0)
	v_add_f32_e32 v0, v38, v0
	v_and_or_b32 v33, v33, s33, v34
	ds_bpermute_b32 v34, v66, v0
	v_and_or_b32 v32, v35, s33, v32
	v_and_or_b32 v31, v31, s33, v37
	v_lshrrev_b32_e32 v30, 16, v30
	v_and_or_b32 v30, v42, s33, v30
	s_waitcnt lgkmcnt(0)
	v_add_f32_e32 v0, v0, v34
	v_lshlrev_b64 v[34:35], 10, v[120:121]
	v_lshl_add_u64 v[34:35], s[16:17], 0, v[34:35]
	v_rcp_f32_e32 v40, v0
	v_lshl_add_u64 v[34:35], v[34:35], 0, s[46:47]
	v_lshlrev_b32_e32 v0, 1, v80
	v_lshl_add_u64 v[38:39], v[34:35], 0, v[0:1]
	ds_read_u16 v46, v145
	ds_read_u16 v47, v145 offset:264
	ds_read_u16 v48, v145 offset:528
	ds_read_u16 v49, v145 offset:792
	ds_read_u16 v50, v145 offset:4224
	ds_read_u16 v51, v145 offset:4488
	ds_read_u16 v52, v145 offset:4752
	ds_read_u16 v53, v145 offset:5016
	ds_read_u16 v54, v145 offset:8448
	ds_read_u16 v55, v145 offset:8712
	ds_read_u16 v56, v145 offset:8976
	ds_read_u16 v57, v145 offset:9240
	ds_read_u16 v58, v145 offset:12672
	ds_read_u16 v59, v145 offset:12936
	ds_read_u16 v60, v145 offset:13200
	s_waitcnt lgkmcnt(7)
	ds_read_u16 v61, v145 offset:13464
	v_lshl_or_b32 v62, v47, 16, v46
	v_lshl_or_b32 v63, v49, 16, v48
	v_lshl_or_b32 v64, v51, 16, v50
	v_lshl_or_b32 v65, v53, 16, v52
	s_nop 1
	v_mfma_f32_16x16x32_bf16 v[34:37], v[62:65], v[2:5], 0
	ds_read_u16 v46, v145 offset:16896
	ds_read_u16 v47, v145 offset:17160
	ds_read_u16 v48, v145 offset:17424
	ds_read_u16 v49, v145 offset:17688
	ds_read_u16 v50, v145 offset:21120
	ds_read_u16 v51, v145 offset:21384
	ds_read_u16 v52, v145 offset:21648
	s_waitcnt lgkmcnt(7)
	ds_read_u16 v53, v145 offset:21912
	v_lshl_or_b32 v42, v55, 16, v54
	v_lshl_or_b32 v43, v57, 16, v56
	v_lshl_or_b32 v44, v59, 16, v58
	v_lshl_or_b32 v45, v61, 16, v60
	s_nop 1
	v_mfma_f32_16x16x32_bf16 v[34:37], v[42:45], v[6:9], v[34:37]
	ds_read_u16 v54, v145 offset:25344
	ds_read_u16 v55, v145 offset:25608
	ds_read_u16 v56, v145 offset:25872
	ds_read_u16 v57, v145 offset:26136
	ds_read_u16 v58, v145 offset:29568
	ds_read_u16 v59, v145 offset:29832
	ds_read_u16 v60, v145 offset:30096
	s_waitcnt lgkmcnt(7)
	ds_read_u16 v61, v145 offset:30360
	v_lshl_or_b32 v62, v47, 16, v46
	v_lshl_or_b32 v63, v49, 16, v48
	v_lshl_or_b32 v64, v51, 16, v50
	v_lshl_or_b32 v65, v53, 16, v52
	s_nop 1
	v_mfma_f32_16x16x32_bf16 v[34:37], v[62:65], v[10:13], v[34:37]
	ds_read_u16 v46, v145 offset:33792
	ds_read_u16 v47, v145 offset:34056
	ds_read_u16 v48, v145 offset:34320
	ds_read_u16 v49, v145 offset:34584
	ds_read_u16 v50, v145 offset:38016
	ds_read_u16 v51, v145 offset:38280
	ds_read_u16 v52, v145 offset:38544
	s_waitcnt lgkmcnt(7)
	ds_read_u16 v53, v145 offset:38808
	v_lshl_or_b32 v42, v55, 16, v54
	v_lshl_or_b32 v43, v57, 16, v56
	v_lshl_or_b32 v44, v59, 16, v58
	v_lshl_or_b32 v45, v61, 16, v60
	s_nop 1
	v_mfma_f32_16x16x32_bf16 v[34:37], v[42:45], v[14:17], v[34:37]
	ds_read_u16 v54, v145 offset:42240
	ds_read_u16 v55, v145 offset:42504
	ds_read_u16 v56, v145 offset:42768
	ds_read_u16 v57, v145 offset:43032
	ds_read_u16 v58, v145 offset:46464
	ds_read_u16 v59, v145 offset:46728
	ds_read_u16 v60, v145 offset:46992
	s_waitcnt lgkmcnt(7)
	ds_read_u16 v61, v145 offset:47256
	v_lshl_or_b32 v62, v47, 16, v46
	v_lshl_or_b32 v63, v49, 16, v48
	v_lshl_or_b32 v64, v51, 16, v50
	v_lshl_or_b32 v65, v53, 16, v52
	s_nop 1
	v_mfma_f32_16x16x32_bf16 v[34:37], v[62:65], v[18:21], v[34:37]
	ds_read_u16 v46, v145 offset:50688
	ds_read_u16 v47, v145 offset:50952
	ds_read_u16 v48, v145 offset:51216
	ds_read_u16 v49, v145 offset:51480
	ds_read_u16 v50, v145 offset:54912
	ds_read_u16 v51, v145 offset:55176
	ds_read_u16 v52, v145 offset:55440
	s_waitcnt lgkmcnt(7)
	ds_read_u16 v53, v145 offset:55704
	v_lshl_or_b32 v42, v55, 16, v54
	v_lshl_or_b32 v43, v57, 16, v56
	v_lshl_or_b32 v44, v59, 16, v58
	v_lshl_or_b32 v45, v61, 16, v60
	s_nop 1
	v_mfma_f32_16x16x32_bf16 v[34:37], v[42:45], v[22:25], v[34:37]
	ds_read_u16 v54, v145 offset:59136
	ds_read_u16 v55, v145 offset:59400
	ds_read_u16 v56, v145 offset:59664
	ds_read_u16 v57, v145 offset:59928
	ds_read_u16 v58, v145 offset:63360
	ds_read_u16 v59, v145 offset:63624
	ds_read_u16 v60, v145 offset:63888
	s_waitcnt lgkmcnt(7)
	ds_read_u16 v61, v145 offset:64152
	v_lshl_or_b32 v62, v47, 16, v46
	v_lshl_or_b32 v63, v49, 16, v48
	v_lshl_or_b32 v64, v51, 16, v50
	v_lshl_or_b32 v65, v53, 16, v52
	s_nop 1
	v_mfma_f32_16x16x32_bf16 v[34:37], v[62:65], v[26:29], v[34:37]
	ds_read_u16 v46, v145 offset:32
	ds_read_u16 v47, v145 offset:296
	ds_read_u16 v48, v145 offset:560
	ds_read_u16 v49, v145 offset:824
	ds_read_u16 v50, v145 offset:4256
	ds_read_u16 v51, v145 offset:4520
	ds_read_u16 v52, v145 offset:4784
	s_waitcnt lgkmcnt(7)
	ds_read_u16 v53, v145 offset:5048
	v_lshl_or_b32 v42, v55, 16, v54
	v_lshl_or_b32 v43, v57, 16, v56
	v_lshl_or_b32 v44, v59, 16, v58
	v_lshl_or_b32 v45, v61, 16, v60
	s_nop 1
	v_mfma_f32_16x16x32_bf16 v[34:37], v[42:45], v[30:33], v[34:37]
	s_and_saveexec_b64 s[24:25], s[8:9]
	s_cbranch_execz .LBB0_127
	s_nop 5
	v_mov_b32_e32 v43, v36
	v_mov_b32_e32 v36, v35
	v_mov_b32_e32 v42, v34
	v_pk_mul_f32 v[34:35], v[40:41], v[36:37] op_sel_hi:[0,1]
	v_pk_mul_f32 v[42:43], v[40:41], v[42:43] op_sel_hi:[0,1]
	v_and_b32_sdwa v37, v35, v202 dst_sel:DWORD dst_unused:UNUSED_PAD src0_sel:WORD_1 src1_sel:DWORD
	v_and_b32_sdwa v41, v34, v202 dst_sel:DWORD dst_unused:UNUSED_PAD src0_sel:WORD_1 src1_sel:DWORD
	v_and_b32_sdwa v0, v43, v202 dst_sel:DWORD dst_unused:UNUSED_PAD src0_sel:WORD_1 src1_sel:DWORD
	v_and_b32_sdwa v36, v42, v202 dst_sel:DWORD dst_unused:UNUSED_PAD src0_sel:WORD_1 src1_sel:DWORD
	v_add3_u32 v35, v35, v37, s60
	v_add3_u32 v34, v34, v41, s60
	v_add3_u32 v36, v42, v36, s60
	v_add3_u32 v0, v43, v0, s60
	v_and_b32_e32 v35, 0xffff0000, v35
	v_and_b32_e32 v34, 0xffff0000, v34
	v_or_b32_sdwa v35, v35, v0 dst_sel:DWORD dst_unused:UNUSED_PAD src0_sel:DWORD src1_sel:WORD_1
	v_or_b32_sdwa v34, v34, v36 dst_sel:DWORD dst_unused:UNUSED_PAD src0_sel:DWORD src1_sel:WORD_1
	global_store_dwordx2 v[38:39], v[34:35], off
